# GEMMs: first K-tile MFMAs take srcC=0 so the 32 accumulator-zeroing MFMAs per tile are removed (all three GEMM loops); attn_combine loads batched
# speedup vs baseline: 1.0059x; 1.0059x over previous
.LBB0_132:
	s_mov_b64 s[12:13], s[88:89]
	v_readlane_b32 s2, v255, 0
	v_readlane_b32 s24, v255, 16
	s_mov_b64 s[0:1], s[94:95]
	v_readlane_b32 s3, v255, 9
	s_add_u32 s0, s12, 0x28600000
	s_addc_u32 s1, s13, 0
	s_sub_i32 s2, s2, s59
	v_mbcnt_lo_u32_b32 v0, -1, 0
	v_mbcnt_hi_u32_b32 v0, -1, v0
	s_mov_b64 s[4:5], -1
	v_lshl_add_u32 v152, s3, 6, v0
	s_ashr_i32 s3, s2, 31
	s_and_b32 s3, s3, s24
	s_add_i32 s25, s3, s2
	v_readlane_b32 s2, v255, 46
	v_readlane_b32 s3, v255, 47
	s_and_b64 vcc, exec, s[2:3]
	s_cbranch_vccz .LBB0_152
	v_mov_b32_e32 v130, v152
	s_cmpk_gt_i32 s25, 0x2bf
	v_readfirstlane_b32 s4, v130
	s_cbranch_scc1 .LBB0_151
	v_mov_b32_e32 v2, v1
	v_mov_b32_e32 v3, v1
	v_mov_b32_e32 v0, v1
	v_mov_b64_e32 v[12:13], v[2:3]
	v_mov_b64_e32 v[10:11], v[0:1]
	s_lshl_b64 s[2:3], s[56:57], 12
	s_add_u32 s48, s0, s2
	s_nop 0
	s_addc_u32 s2, s1, s3
	v_readlane_b32 s3, v255, 45
	s_nop 0
	s_mul_i32 s3, s3, 0x2c00000
	s_add_u32 s3, s12, s3
	s_nop 0
	s_addc_u32 s5, s13, 0
	s_add_u32 s8, s3, 0x200000
	s_nop 0
	s_addc_u32 s3, s5, 0
	s_ashr_i32 s5, s4, 6
	s_nop 0
	s_lshl_b32 s9, s5, 3
	v_bfe_u32 v2, v130, 3, 3
	s_nop 0
	v_or_b32_e32 v4, s9, v2
	v_and_b32_e32 v0, 63, v130
	s_nop 0
	v_lshrrev_b32_e32 v5, 1, v4
	s_lshl_b32 s10, s5, 1
	s_nop 0
	v_bfe_u32 v3, v0, 3, 2
	v_xor_b32_e32 v5, v5, v130
	s_nop 0
	v_lshlrev_b32_e32 v6, 1, v4
	v_and_or_b32 v3, s10, 4, v3
	s_nop 0
	v_lshlrev_b32_e32 v5, 4, v5
	s_and_b32 s10, s9, 0xfffe0
	s_nop 0
	v_and_b32_e32 v6, 24, v6
	s_add_i32 s9, s9, 64
	s_nop 0
	s_and_b32 s49, s2, 0xffff
	s_ashr_i32 s2, s25, 31
	v_and_b32_e32 v5, 0x70, v5
	v_or3_b32 v6, s10, v6, v3
	v_or_b32_e32 v2, s9, v2
	s_nop 0
	s_lshr_b32 s14, s2, 29
	v_lshl_or_b32 v153, v4, 12, v5
	v_lshl_or_b32 v154, v6, 12, v5
	v_lshlrev_b32_e32 v5, 1, v2
	s_nop 0
	s_add_i32 s14, s25, s14
	s_and_b32 s9, s9, 0xfffe0
	v_and_b32_e32 v5, 24, v5
	s_nop 0
	s_ashr_i32 s15, s14, 3
	s_and_b32 s14, s14, -8
	s_ashr_i32 s20, s4, 8
	v_or3_b32 v3, s9, v5, v3
	s_nop 0
	s_and_b32 s9, s3, 0xffff
	s_lshl_b32 s3, s5, 10
	s_sub_i32 s14, s25, s14
	s_nop 0
	s_cmp_lt_i32 s14, 0
	s_movk_i32 s16, 0x59
	s_nop 0
	s_cselect_b32 s16, s16, 0x58
	s_mul_i32 s14, s14, s16
	s_nop 0
	v_lshrrev_b32_e32 v4, 1, v2
	s_add_i32 s14, s14, s15
	s_nop 0
	v_xor_b32_e32 v4, v4, v130
	s_mul_hi_i32 s15, s14, 0x2e8ba2e9
	s_nop 0
	v_lshlrev_b32_e32 v4, 4, v4
	s_lshr_b32 s16, s15, 31
	s_nop 0
	s_ashr_i32 s15, s15, 5
	v_and_b32_e32 v4, 0x70, v4
	s_nop 0
	s_add_i32 s15, s15, s16
	v_lshl_or_b32 v155, v2, 12, v4
	v_lshl_or_b32 v156, v3, 12, v4
	s_nop 0
	s_lshl_b32 s16, s15, 2
	s_mulk_i32 s15, 0xb0
	s_nop 0
	s_sub_i32 s14, s14, s15
	s_bfe_u32 s15, s14, 0x2001d
	s_nop 0
	s_add_i32 s15, s14, s15
	s_sext_i32_i16 s17, s15
	s_nop 0
	s_add_i32 s3, s3, 0
	s_and_b32 s15, s15, 0xfffc
	s_nop 0
	s_ashr_i32 s53, s17, 2
	s_add_i32 s26, s3, 0x10000
	s_nop 0
	s_mov_b32 s10, s50
	s_mov_b32 s11, s51
	s_sub_i32 s14, s14, s15
	s_nop 0
	s_lshl_b32 s60, s53, 20
	s_mov_b32 m0, s26
	s_add_i32 s27, s3, 0x12000
	s_sext_i32_i16 s14, s14
	s_nop 0
	buffer_load_dwordx4 v154, s[8:11], s60 offen lds
	s_mov_b32 m0, s27
	s_add_i32 s28, s3, 0x14000
	s_add_i32 s58, s16, s14
	buffer_load_dwordx4 v156, s[8:11], s60 offen lds
	s_or_b32 s14, s60, 0x80000
	s_mov_b32 m0, s28
	s_add_i32 s29, s3, 0x16000
	buffer_load_dwordx4 v154, s[8:11], s14 offen lds
	s_mov_b32 m0, s29
	s_lshl_b32 s61, s58, 20
	buffer_load_dwordx4 v156, s[8:11], s14 offen lds
	s_mov_b32 m0, s3
	s_add_i32 s30, s3, 0x2000
	buffer_load_dwordx4 v153, s[48:51], s61 offen lds
	s_mov_b32 m0, s30
	s_add_i32 s31, s3, 0x4000
	buffer_load_dwordx4 v155, s[48:51], s61 offen lds
	s_or_b32 s10, s61, 0x80000
	s_mov_b32 m0, s31
	s_add_i32 s34, s3, 0x6000
	buffer_load_dwordx4 v153, s[48:51], s10 offen lds
	s_mov_b32 m0, s34
	s_nop 0
	buffer_load_dwordx4 v155, s[48:51], s10 offen lds
	s_cmp_eq_u32 s20, 1
	s_cselect_b64 s[14:15], -1, 0
	s_cmp_lg_u32 s20, 1
	s_cbranch_scc1 .LBB0_136
	s_barrier

.Lc0s_first:
	s_add_i32 s62, s58, 0xfff80080
	s_and_b64 s[10:11], s[10:11], exec
	s_cselect_b32 s78, s54, s62
	s_cselect_b32 s62, s55, s60
	s_add_i32 s10, 0, 0x10000
	v_add_u32_e32 v0, s10, v157
	v_add_u32_e32 v147, s10, v158
	s_add_i32 s10, 0, 0x14000
	ds_read_b128 v[164:167], v0
	ds_read_b128 v[168:171], v0 offset:2048
	ds_read_b128 v[172:175], v147
	ds_read_b128 v[176:179], v147 offset:2048
	v_add_u32_e32 v0, s10, v157
	v_add_u32_e32 v147, s10, v158
	ds_read_b128 v[180:183], v0
	ds_read_b128 v[184:187], v0 offset:2048
	ds_read_b128 v[188:191], v147
	ds_read_b128 v[192:195], v147 offset:2048
	s_or_b32 s64, s78, 0x80
	s_or_b32 s65, s62, 0x80
	s_mov_b32 m0, s41
	ds_read_b128 v[196:199], v161
	ds_read_b128 v[204:207], v161 offset:2048
	ds_read_b128 v[208:211], v162
	ds_read_b128 v[212:215], v162 offset:2048
	ds_read_b128 v[216:219], v161 offset:4096
	ds_read_b128 v[220:223], v161 offset:6144
	ds_read_b128 v[224:227], v162 offset:4096
	ds_read_b128 v[228:231], v162 offset:6144
	buffer_load_dwordx4 v153, s[48:51], s58 offen lds
	s_mov_b32 m0, s42
	s_nop 0
	buffer_load_dwordx4 v155, s[48:51], s58 offen lds
	s_waitcnt vmcnt(8)
	s_waitcnt lgkmcnt(0)
	s_barrier
	s_setprio 1
	s_waitcnt lgkmcnt(0)
	v_mfma_f32_16x16x32_f16 v[118:121], v[164:167], v[196:199], 0
	v_mfma_f32_16x16x32_f16 v[110:113], v[168:171], v[196:199], 0
	v_mfma_f32_16x16x32_f16 v[102:105], v[164:167], v[204:207], 0
	v_mfma_f32_16x16x32_f16 v[94:97], v[168:171], v[204:207], 0
	v_mfma_f32_16x16x32_f16 v[86:89], v[164:167], v[216:219], 0
	v_mfma_f32_16x16x32_f16 v[78:81], v[168:171], v[216:219], 0
	v_mfma_f32_16x16x32_f16 v[66:69], v[164:167], v[220:223], 0
	v_mfma_f32_16x16x32_f16 v[58:61], v[168:171], v[220:223], 0
	v_mfma_f32_16x16x32_f16 v[118:121], v[172:175], v[208:211], v[118:121]
	v_mfma_f32_16x16x32_f16 v[110:113], v[176:179], v[208:211], v[110:113]
	v_mfma_f32_16x16x32_f16 v[102:105], v[172:175], v[212:215], v[102:105]
	v_mfma_f32_16x16x32_f16 v[94:97], v[176:179], v[212:215], v[94:97]
	v_mfma_f32_16x16x32_f16 v[86:89], v[172:175], v[224:227], v[86:89]
	v_mfma_f32_16x16x32_f16 v[78:81], v[176:179], v[224:227], v[78:81]
	v_mfma_f32_16x16x32_f16 v[66:69], v[172:175], v[228:231], v[66:69]
	v_mfma_f32_16x16x32_f16 v[58:61], v[176:179], v[228:231], v[58:61]
	s_setprio 0
	s_setprio 1
	v_mfma_f32_16x16x32_f16 v[126:129], v[180:183], v[196:199], 0
	v_mfma_f32_16x16x32_f16 v[122:125], v[184:187], v[196:199], 0
	v_mfma_f32_16x16x32_f16 v[114:117], v[180:183], v[204:207], 0
	v_mfma_f32_16x16x32_f16 v[106:109], v[184:187], v[204:207], 0
	v_mfma_f32_16x16x32_f16 v[98:101], v[180:183], v[216:219], 0
	v_mfma_f32_16x16x32_f16 v[90:93], v[184:187], v[216:219], 0
	v_mfma_f32_16x16x32_f16 v[82:85], v[180:183], v[220:223], 0
	v_mfma_f32_16x16x32_f16 v[74:77], v[184:187], v[220:223], 0
	v_mfma_f32_16x16x32_f16 v[126:129], v[188:191], v[208:211], v[126:129]
	v_mfma_f32_16x16x32_f16 v[122:125], v[192:195], v[208:211], v[122:125]
	v_mfma_f32_16x16x32_f16 v[114:117], v[188:191], v[212:215], v[114:117]
	v_mfma_f32_16x16x32_f16 v[106:109], v[192:195], v[212:215], v[106:109]
	v_mfma_f32_16x16x32_f16 v[98:101], v[188:191], v[224:227], v[98:101]
	v_mfma_f32_16x16x32_f16 v[90:93], v[192:195], v[224:227], v[90:93]
	v_mfma_f32_16x16x32_f16 v[82:85], v[188:191], v[228:231], v[82:85]
	v_mfma_f32_16x16x32_f16 v[74:77], v[192:195], v[228:231], v[74:77]
	s_setprio 0
	s_barrier
	s_mov_b32 m0, s26
	s_mov_b32 s10, s50
	s_mov_b32 s11, s51
	ds_read_b128 v[196:199], v161 offset:16384
	ds_read_b128 v[204:207], v161 offset:18432
	ds_read_b128 v[208:211], v162 offset:16384
	ds_read_b128 v[212:215], v162 offset:18432
	ds_read_b128 v[216:219], v161 offset:20480
	ds_read_b128 v[220:223], v161 offset:22528
	ds_read_b128 v[224:227], v162 offset:20480
	ds_read_b128 v[228:231], v162 offset:22528
	buffer_load_dwordx4 v154, s[8:11], s62 offen lds
	s_mov_b32 m0, s27
	s_add_i32 s81, s62, 0x80000
	buffer_load_dwordx4 v156, s[8:11], s62 offen lds
	s_mov_b32 m0, s28
	s_nop 0
	buffer_load_dwordx4 v154, s[8:11], s81 offen lds
	s_mov_b32 m0, s29
	s_nop 0
	buffer_load_dwordx4 v156, s[8:11], s81 offen lds
	s_mov_b32 m0, s3
	s_nop 0
	buffer_load_dwordx4 v153, s[48:51], s78 offen lds
	s_mov_b32 m0, s30
	s_nop 0
	buffer_load_dwordx4 v155, s[48:51], s78 offen lds
	s_waitcnt vmcnt(8)
	s_waitcnt lgkmcnt(0)
	s_barrier
	s_setprio 1
	s_waitcnt lgkmcnt(0)
	v_mfma_f32_16x16x32_f16 v[54:57], v[164:167], v[196:199], 0
	v_mfma_f32_16x16x32_f16 v[46:49], v[168:171], v[196:199], 0
	v_mfma_f32_16x16x32_f16 v[38:41], v[164:167], v[204:207], 0
	v_mfma_f32_16x16x32_f16 v[30:33], v[168:171], v[204:207], 0
	v_mfma_f32_16x16x32_f16 v[22:25], v[164:167], v[216:219], 0
	v_mfma_f32_16x16x32_f16 v[14:17], v[168:171], v[216:219], 0
	v_mfma_f32_16x16x32_f16 v[6:9], v[164:167], v[220:223], 0
	v_mfma_f32_16x16x32_f16 v[2:5], v[168:171], v[220:223], 0
	v_mfma_f32_16x16x32_f16 v[54:57], v[172:175], v[208:211], v[54:57]
	v_mfma_f32_16x16x32_f16 v[46:49], v[176:179], v[208:211], v[46:49]
	v_mfma_f32_16x16x32_f16 v[38:41], v[172:175], v[212:215], v[38:41]
	v_mfma_f32_16x16x32_f16 v[30:33], v[176:179], v[212:215], v[30:33]
	v_mfma_f32_16x16x32_f16 v[22:25], v[172:175], v[224:227], v[22:25]
	v_mfma_f32_16x16x32_f16 v[14:17], v[176:179], v[224:227], v[14:17]
	v_mfma_f32_16x16x32_f16 v[6:9], v[172:175], v[228:231], v[6:9]
	v_mfma_f32_16x16x32_f16 v[2:5], v[176:179], v[228:231], v[2:5]
	s_setprio 0
	s_setprio 1
	v_mfma_f32_16x16x32_f16 v[70:73], v[180:183], v[196:199], 0
	v_mfma_f32_16x16x32_f16 v[62:65], v[184:187], v[196:199], 0
	v_mfma_f32_16x16x32_f16 v[50:53], v[180:183], v[204:207], 0
	v_mfma_f32_16x16x32_f16 v[42:45], v[184:187], v[204:207], 0
	v_mfma_f32_16x16x32_f16 v[34:37], v[180:183], v[216:219], 0
	v_mfma_f32_16x16x32_f16 v[26:29], v[184:187], v[216:219], 0
	v_mfma_f32_16x16x32_f16 v[18:21], v[180:183], v[220:223], 0
	v_mfma_f32_16x16x32_f16 v[10:13], v[184:187], v[220:223], 0
	v_mfma_f32_16x16x32_f16 v[70:73], v[188:191], v[208:211], v[70:73]
	v_mfma_f32_16x16x32_f16 v[62:65], v[192:195], v[208:211], v[62:65]
	v_mfma_f32_16x16x32_f16 v[50:53], v[188:191], v[212:215], v[50:53]
	v_mfma_f32_16x16x32_f16 v[42:45], v[192:195], v[212:215], v[42:45]
	v_mfma_f32_16x16x32_f16 v[34:37], v[188:191], v[224:227], v[34:37]
	v_mfma_f32_16x16x32_f16 v[26:29], v[192:195], v[224:227], v[26:29]
	v_mfma_f32_16x16x32_f16 v[18:21], v[188:191], v[228:231], v[18:21]
	v_mfma_f32_16x16x32_f16 v[10:13], v[192:195], v[228:231], v[10:13]
	s_setprio 0
	s_barrier
	s_add_i32 s81, 0, 0x18000
	v_add_u32_e32 v0, s81, v157
	v_add_u32_e32 v147, s81, v158
	s_add_i32 s81, 0, 0x1c000
	ds_read_b128 v[164:167], v0
	ds_read_b128 v[168:171], v0 offset:2048
	ds_read_b128 v[172:175], v147
	ds_read_b128 v[176:179], v147 offset:2048
	v_add_u32_e32 v0, s81, v157
	v_add_u32_e32 v147, s81, v158
	ds_read_b128 v[180:183], v0
	ds_read_b128 v[184:187], v0 offset:2048
	ds_read_b128 v[188:191], v147
	ds_read_b128 v[192:195], v147 offset:2048
	s_add_i32 s78, s78, 0x80000
	s_mov_b32 m0, s31
	ds_read_b128 v[196:199], v161 offset:32768
	ds_read_b128 v[204:207], v161 offset:34816
	ds_read_b128 v[208:211], v162 offset:32768
	ds_read_b128 v[212:215], v162 offset:34816
	ds_read_b128 v[216:219], v161 offset:36864
	ds_read_b128 v[220:223], v161 offset:38912
	ds_read_b128 v[224:227], v162 offset:36864
	ds_read_b128 v[228:231], v162 offset:38912
	buffer_load_dwordx4 v153, s[48:51], s78 offen lds
	s_mov_b32 m0, s34
	s_nop 0
	buffer_load_dwordx4 v155, s[48:51], s78 offen lds
	s_waitcnt vmcnt(8)
	s_waitcnt lgkmcnt(0)
	s_barrier
	s_setprio 1
	s_waitcnt lgkmcnt(0)
	v_mfma_f32_16x16x32_f16 v[118:121], v[164:167], v[196:199], v[118:121]
	v_mfma_f32_16x16x32_f16 v[110:113], v[168:171], v[196:199], v[110:113]
	v_mfma_f32_16x16x32_f16 v[102:105], v[164:167], v[204:207], v[102:105]
	v_mfma_f32_16x16x32_f16 v[94:97], v[168:171], v[204:207], v[94:97]
	v_mfma_f32_16x16x32_f16 v[86:89], v[164:167], v[216:219], v[86:89]
	v_mfma_f32_16x16x32_f16 v[78:81], v[168:171], v[216:219], v[78:81]
	v_mfma_f32_16x16x32_f16 v[66:69], v[164:167], v[220:223], v[66:69]
	v_mfma_f32_16x16x32_f16 v[58:61], v[168:171], v[220:223], v[58:61]
	v_mfma_f32_16x16x32_f16 v[118:121], v[172:175], v[208:211], v[118:121]
	v_mfma_f32_16x16x32_f16 v[110:113], v[176:179], v[208:211], v[110:113]
	v_mfma_f32_16x16x32_f16 v[102:105], v[172:175], v[212:215], v[102:105]
	v_mfma_f32_16x16x32_f16 v[94:97], v[176:179], v[212:215], v[94:97]
	v_mfma_f32_16x16x32_f16 v[86:89], v[172:175], v[224:227], v[86:89]
	v_mfma_f32_16x16x32_f16 v[78:81], v[176:179], v[224:227], v[78:81]
	v_mfma_f32_16x16x32_f16 v[66:69], v[172:175], v[228:231], v[66:69]
	v_mfma_f32_16x16x32_f16 v[58:61], v[176:179], v[228:231], v[58:61]
	s_setprio 0
	s_setprio 1
	v_mfma_f32_16x16x32_f16 v[126:129], v[180:183], v[196:199], v[126:129]
	v_mfma_f32_16x16x32_f16 v[122:125], v[184:187], v[196:199], v[122:125]
	v_mfma_f32_16x16x32_f16 v[114:117], v[180:183], v[204:207], v[114:117]
	v_mfma_f32_16x16x32_f16 v[106:109], v[184:187], v[204:207], v[106:109]
	v_mfma_f32_16x16x32_f16 v[98:101], v[180:183], v[216:219], v[98:101]
	v_mfma_f32_16x16x32_f16 v[90:93], v[184:187], v[216:219], v[90:93]
	v_mfma_f32_16x16x32_f16 v[82:85], v[180:183], v[220:223], v[82:85]
	v_mfma_f32_16x16x32_f16 v[74:77], v[184:187], v[220:223], v[74:77]
	v_mfma_f32_16x16x32_f16 v[126:129], v[188:191], v[208:211], v[126:129]
	v_mfma_f32_16x16x32_f16 v[122:125], v[192:195], v[208:211], v[122:125]
	v_mfma_f32_16x16x32_f16 v[114:117], v[188:191], v[212:215], v[114:117]
	v_mfma_f32_16x16x32_f16 v[106:109], v[192:195], v[212:215], v[106:109]
	v_mfma_f32_16x16x32_f16 v[98:101], v[188:191], v[224:227], v[98:101]
	v_mfma_f32_16x16x32_f16 v[90:93], v[192:195], v[224:227], v[90:93]
	v_mfma_f32_16x16x32_f16 v[82:85], v[188:191], v[228:231], v[82:85]
	v_mfma_f32_16x16x32_f16 v[74:77], v[192:195], v[228:231], v[74:77]
	s_setprio 0
	s_barrier
	s_mov_b32 m0, s35
	ds_read_b128 v[196:199], v161 offset:49152
	ds_read_b128 v[204:207], v161 offset:51200
	ds_read_b128 v[208:211], v162 offset:49152
	ds_read_b128 v[212:215], v162 offset:51200
	ds_read_b128 v[216:219], v161 offset:53248
	ds_read_b128 v[220:223], v161 offset:55296
	ds_read_b128 v[224:227], v162 offset:53248
	ds_read_b128 v[228:231], v162 offset:55296
	buffer_load_dwordx4 v154, s[8:11], s65 offen lds
	s_mov_b32 m0, s36
	s_add_i32 s62, s62, 0x80080
	buffer_load_dwordx4 v156, s[8:11], s65 offen lds
	s_mov_b32 m0, s39
	s_nop 0
	buffer_load_dwordx4 v154, s[8:11], s62 offen lds
	s_mov_b32 m0, s40
	s_nop 0
	buffer_load_dwordx4 v156, s[8:11], s62 offen lds
	s_mov_b32 m0, s37
	s_nop 0
	buffer_load_dwordx4 v153, s[48:51], s64 offen lds
	s_mov_b32 m0, s38
	s_nop 0
	buffer_load_dwordx4 v155, s[48:51], s64 offen lds
	s_waitcnt vmcnt(8)
	s_waitcnt lgkmcnt(0)
	s_barrier
	s_setprio 1
	s_waitcnt lgkmcnt(0)
	v_mfma_f32_16x16x32_f16 v[54:57], v[164:167], v[196:199], v[54:57]
	v_mfma_f32_16x16x32_f16 v[46:49], v[168:171], v[196:199], v[46:49]
	v_mfma_f32_16x16x32_f16 v[38:41], v[164:167], v[204:207], v[38:41]
	v_mfma_f32_16x16x32_f16 v[30:33], v[168:171], v[204:207], v[30:33]
	v_mfma_f32_16x16x32_f16 v[22:25], v[164:167], v[216:219], v[22:25]
	v_mfma_f32_16x16x32_f16 v[14:17], v[168:171], v[216:219], v[14:17]
	v_mfma_f32_16x16x32_f16 v[6:9], v[164:167], v[220:223], v[6:9]
	v_mfma_f32_16x16x32_f16 v[2:5], v[168:171], v[220:223], v[2:5]
	v_mfma_f32_16x16x32_f16 v[54:57], v[172:175], v[208:211], v[54:57]
	v_mfma_f32_16x16x32_f16 v[46:49], v[176:179], v[208:211], v[46:49]
	v_mfma_f32_16x16x32_f16 v[38:41], v[172:175], v[212:215], v[38:41]
	v_mfma_f32_16x16x32_f16 v[30:33], v[176:179], v[212:215], v[30:33]
	v_mfma_f32_16x16x32_f16 v[22:25], v[172:175], v[224:227], v[22:25]
	v_mfma_f32_16x16x32_f16 v[14:17], v[176:179], v[224:227], v[14:17]
	v_mfma_f32_16x16x32_f16 v[6:9], v[172:175], v[228:231], v[6:9]
	v_mfma_f32_16x16x32_f16 v[2:5], v[176:179], v[228:231], v[2:5]
	s_setprio 0
	s_setprio 1
	v_mfma_f32_16x16x32_f16 v[70:73], v[180:183], v[196:199], v[70:73]
	v_mfma_f32_16x16x32_f16 v[62:65], v[184:187], v[196:199], v[62:65]
	v_mfma_f32_16x16x32_f16 v[50:53], v[180:183], v[204:207], v[50:53]
	v_mfma_f32_16x16x32_f16 v[42:45], v[184:187], v[204:207], v[42:45]
	v_mfma_f32_16x16x32_f16 v[34:37], v[180:183], v[216:219], v[34:37]
	v_mfma_f32_16x16x32_f16 v[26:29], v[184:187], v[216:219], v[26:29]
	v_mfma_f32_16x16x32_f16 v[18:21], v[180:183], v[220:223], v[18:21]
	v_mfma_f32_16x16x32_f16 v[10:13], v[184:187], v[220:223], v[10:13]
	v_mfma_f32_16x16x32_f16 v[70:73], v[188:191], v[208:211], v[70:73]
	v_mfma_f32_16x16x32_f16 v[62:65], v[192:195], v[208:211], v[62:65]
	v_mfma_f32_16x16x32_f16 v[50:53], v[188:191], v[212:215], v[50:53]
	v_mfma_f32_16x16x32_f16 v[42:45], v[192:195], v[212:215], v[42:45]
	v_mfma_f32_16x16x32_f16 v[34:37], v[188:191], v[224:227], v[34:37]
	v_mfma_f32_16x16x32_f16 v[26:29], v[192:195], v[224:227], v[26:29]
	v_mfma_f32_16x16x32_f16 v[18:21], v[188:191], v[228:231], v[18:21]
	v_mfma_f32_16x16x32_f16 v[10:13], v[192:195], v[228:231], v[10:13]
	s_setprio 0
	s_barrier
	s_branch .Lc0s_tail
.LBB0_142:
	s_cmp_eq_u32 s61, -2
	s_cbranch_scc1 .Lc0s_first
	s_add_i32 s62, s58, 0xfff80080
	s_and_b64 s[10:11], s[10:11], exec
	s_cselect_b32 s78, s54, s62
	s_cselect_b32 s62, s55, s60
	s_add_i32 s10, 0, 0x10000
	v_add_u32_e32 v0, s10, v157
	v_add_u32_e32 v147, s10, v158
	s_add_i32 s10, 0, 0x14000
	ds_read_b128 v[164:167], v0
	ds_read_b128 v[168:171], v0 offset:2048
	ds_read_b128 v[172:175], v147
	ds_read_b128 v[176:179], v147 offset:2048
	v_add_u32_e32 v0, s10, v157
	v_add_u32_e32 v147, s10, v158
	ds_read_b128 v[180:183], v0
	ds_read_b128 v[184:187], v0 offset:2048
	ds_read_b128 v[188:191], v147
	ds_read_b128 v[192:195], v147 offset:2048
	s_or_b32 s64, s78, 0x80
	s_or_b32 s65, s62, 0x80
	s_mov_b32 m0, s41
	ds_read_b128 v[196:199], v161
	ds_read_b128 v[204:207], v161 offset:2048
	ds_read_b128 v[208:211], v162
	ds_read_b128 v[212:215], v162 offset:2048
	ds_read_b128 v[216:219], v161 offset:4096
	ds_read_b128 v[220:223], v161 offset:6144
	ds_read_b128 v[224:227], v162 offset:4096
	ds_read_b128 v[228:231], v162 offset:6144
	buffer_load_dwordx4 v153, s[48:51], s58 offen lds
	s_mov_b32 m0, s42
	s_nop 0
	buffer_load_dwordx4 v155, s[48:51], s58 offen lds
	s_waitcnt vmcnt(8)
	s_waitcnt lgkmcnt(0)
	s_barrier
	s_setprio 1
	s_waitcnt lgkmcnt(0)
	v_mfma_f32_16x16x32_f16 v[118:121], v[164:167], v[196:199], v[118:121]
	v_mfma_f32_16x16x32_f16 v[110:113], v[168:171], v[196:199], v[110:113]
	v_mfma_f32_16x16x32_f16 v[102:105], v[164:167], v[204:207], v[102:105]
	v_mfma_f32_16x16x32_f16 v[94:97], v[168:171], v[204:207], v[94:97]
	v_mfma_f32_16x16x32_f16 v[86:89], v[164:167], v[216:219], v[86:89]
	v_mfma_f32_16x16x32_f16 v[78:81], v[168:171], v[216:219], v[78:81]
	v_mfma_f32_16x16x32_f16 v[66:69], v[164:167], v[220:223], v[66:69]
	v_mfma_f32_16x16x32_f16 v[58:61], v[168:171], v[220:223], v[58:61]
	v_mfma_f32_16x16x32_f16 v[118:121], v[172:175], v[208:211], v[118:121]
	v_mfma_f32_16x16x32_f16 v[110:113], v[176:179], v[208:211], v[110:113]
	v_mfma_f32_16x16x32_f16 v[102:105], v[172:175], v[212:215], v[102:105]
	v_mfma_f32_16x16x32_f16 v[94:97], v[176:179], v[212:215], v[94:97]
	v_mfma_f32_16x16x32_f16 v[86:89], v[172:175], v[224:227], v[86:89]
	v_mfma_f32_16x16x32_f16 v[78:81], v[176:179], v[224:227], v[78:81]
	v_mfma_f32_16x16x32_f16 v[66:69], v[172:175], v[228:231], v[66:69]
	v_mfma_f32_16x16x32_f16 v[58:61], v[176:179], v[228:231], v[58:61]
	s_setprio 0
	s_setprio 1
	v_mfma_f32_16x16x32_f16 v[126:129], v[180:183], v[196:199], v[126:129]
	v_mfma_f32_16x16x32_f16 v[122:125], v[184:187], v[196:199], v[122:125]
	v_mfma_f32_16x16x32_f16 v[114:117], v[180:183], v[204:207], v[114:117]
	v_mfma_f32_16x16x32_f16 v[106:109], v[184:187], v[204:207], v[106:109]
	v_mfma_f32_16x16x32_f16 v[98:101], v[180:183], v[216:219], v[98:101]
	v_mfma_f32_16x16x32_f16 v[90:93], v[184:187], v[216:219], v[90:93]
	v_mfma_f32_16x16x32_f16 v[82:85], v[180:183], v[220:223], v[82:85]
	v_mfma_f32_16x16x32_f16 v[74:77], v[184:187], v[220:223], v[74:77]
	v_mfma_f32_16x16x32_f16 v[126:129], v[188:191], v[208:211], v[126:129]
	v_mfma_f32_16x16x32_f16 v[122:125], v[192:195], v[208:211], v[122:125]
	v_mfma_f32_16x16x32_f16 v[114:117], v[188:191], v[212:215], v[114:117]
	v_mfma_f32_16x16x32_f16 v[106:109], v[192:195], v[212:215], v[106:109]
	v_mfma_f32_16x16x32_f16 v[98:101], v[188:191], v[224:227], v[98:101]
	v_mfma_f32_16x16x32_f16 v[90:93], v[192:195], v[224:227], v[90:93]
	v_mfma_f32_16x16x32_f16 v[82:85], v[188:191], v[228:231], v[82:85]
	v_mfma_f32_16x16x32_f16 v[74:77], v[192:195], v[228:231], v[74:77]
	s_setprio 0
	s_barrier
	s_mov_b32 m0, s26
	s_mov_b32 s10, s50
	s_mov_b32 s11, s51
	ds_read_b128 v[196:199], v161 offset:16384
	ds_read_b128 v[204:207], v161 offset:18432
	ds_read_b128 v[208:211], v162 offset:16384
	ds_read_b128 v[212:215], v162 offset:18432
	ds_read_b128 v[216:219], v161 offset:20480
	ds_read_b128 v[220:223], v161 offset:22528
	ds_read_b128 v[224:227], v162 offset:20480
	ds_read_b128 v[228:231], v162 offset:22528
	buffer_load_dwordx4 v154, s[8:11], s62 offen lds
	s_mov_b32 m0, s27
	s_add_i32 s81, s62, 0x80000
	buffer_load_dwordx4 v156, s[8:11], s62 offen lds
	s_mov_b32 m0, s28
	s_nop 0
	buffer_load_dwordx4 v154, s[8:11], s81 offen lds
	s_mov_b32 m0, s29
	s_nop 0
	buffer_load_dwordx4 v156, s[8:11], s81 offen lds
	s_mov_b32 m0, s3
	s_nop 0
	buffer_load_dwordx4 v153, s[48:51], s78 offen lds
	s_mov_b32 m0, s30
	s_nop 0
	buffer_load_dwordx4 v155, s[48:51], s78 offen lds
	s_waitcnt vmcnt(8)
	s_waitcnt lgkmcnt(0)
	s_barrier
	s_setprio 1
	s_waitcnt lgkmcnt(0)
	v_mfma_f32_16x16x32_f16 v[54:57], v[164:167], v[196:199], v[54:57]
	v_mfma_f32_16x16x32_f16 v[46:49], v[168:171], v[196:199], v[46:49]
	v_mfma_f32_16x16x32_f16 v[38:41], v[164:167], v[204:207], v[38:41]
	v_mfma_f32_16x16x32_f16 v[30:33], v[168:171], v[204:207], v[30:33]
	v_mfma_f32_16x16x32_f16 v[22:25], v[164:167], v[216:219], v[22:25]
	v_mfma_f32_16x16x32_f16 v[14:17], v[168:171], v[216:219], v[14:17]
	v_mfma_f32_16x16x32_f16 v[6:9], v[164:167], v[220:223], v[6:9]
	v_mfma_f32_16x16x32_f16 v[2:5], v[168:171], v[220:223], v[2:5]
	v_mfma_f32_16x16x32_f16 v[54:57], v[172:175], v[208:211], v[54:57]
	v_mfma_f32_16x16x32_f16 v[46:49], v[176:179], v[208:211], v[46:49]
	v_mfma_f32_16x16x32_f16 v[38:41], v[172:175], v[212:215], v[38:41]
	v_mfma_f32_16x16x32_f16 v[30:33], v[176:179], v[212:215], v[30:33]
	v_mfma_f32_16x16x32_f16 v[22:25], v[172:175], v[224:227], v[22:25]
	v_mfma_f32_16x16x32_f16 v[14:17], v[176:179], v[224:227], v[14:17]
	v_mfma_f32_16x16x32_f16 v[6:9], v[172:175], v[228:231], v[6:9]
	v_mfma_f32_16x16x32_f16 v[2:5], v[176:179], v[228:231], v[2:5]
	s_setprio 0
	s_setprio 1
	v_mfma_f32_16x16x32_f16 v[70:73], v[180:183], v[196:199], v[70:73]
	v_mfma_f32_16x16x32_f16 v[62:65], v[184:187], v[196:199], v[62:65]
	v_mfma_f32_16x16x32_f16 v[50:53], v[180:183], v[204:207], v[50:53]
	v_mfma_f32_16x16x32_f16 v[42:45], v[184:187], v[204:207], v[42:45]
	v_mfma_f32_16x16x32_f16 v[34:37], v[180:183], v[216:219], v[34:37]
	v_mfma_f32_16x16x32_f16 v[26:29], v[184:187], v[216:219], v[26:29]
	v_mfma_f32_16x16x32_f16 v[18:21], v[180:183], v[220:223], v[18:21]
	v_mfma_f32_16x16x32_f16 v[10:13], v[184:187], v[220:223], v[10:13]
	v_mfma_f32_16x16x32_f16 v[70:73], v[188:191], v[208:211], v[70:73]
	v_mfma_f32_16x16x32_f16 v[62:65], v[192:195], v[208:211], v[62:65]
	v_mfma_f32_16x16x32_f16 v[50:53], v[188:191], v[212:215], v[50:53]
	v_mfma_f32_16x16x32_f16 v[42:45], v[192:195], v[212:215], v[42:45]
	v_mfma_f32_16x16x32_f16 v[34:37], v[188:191], v[224:227], v[34:37]
	v_mfma_f32_16x16x32_f16 v[26:29], v[192:195], v[224:227], v[26:29]
	v_mfma_f32_16x16x32_f16 v[18:21], v[188:191], v[228:231], v[18:21]
	v_mfma_f32_16x16x32_f16 v[10:13], v[192:195], v[228:231], v[10:13]
	s_setprio 0
	s_barrier
	s_add_i32 s81, 0, 0x18000
	v_add_u32_e32 v0, s81, v157
	v_add_u32_e32 v147, s81, v158
	s_add_i32 s81, 0, 0x1c000
	ds_read_b128 v[164:167], v0
	ds_read_b128 v[168:171], v0 offset:2048
	ds_read_b128 v[172:175], v147
	ds_read_b128 v[176:179], v147 offset:2048
	v_add_u32_e32 v0, s81, v157
	v_add_u32_e32 v147, s81, v158
	ds_read_b128 v[180:183], v0
	ds_read_b128 v[184:187], v0 offset:2048
	ds_read_b128 v[188:191], v147
	ds_read_b128 v[192:195], v147 offset:2048
	s_add_i32 s78, s78, 0x80000
	s_mov_b32 m0, s31
	ds_read_b128 v[196:199], v161 offset:32768
	ds_read_b128 v[204:207], v161 offset:34816
	ds_read_b128 v[208:211], v162 offset:32768
	ds_read_b128 v[212:215], v162 offset:34816
	ds_read_b128 v[216:219], v161 offset:36864
	ds_read_b128 v[220:223], v161 offset:38912
	ds_read_b128 v[224:227], v162 offset:36864
	ds_read_b128 v[228:231], v162 offset:38912
	buffer_load_dwordx4 v153, s[48:51], s78 offen lds
	s_mov_b32 m0, s34
	s_nop 0
	buffer_load_dwordx4 v155, s[48:51], s78 offen lds
	s_waitcnt vmcnt(8)
	s_waitcnt lgkmcnt(0)
	s_barrier
	s_setprio 1
	s_waitcnt lgkmcnt(0)
	v_mfma_f32_16x16x32_f16 v[118:121], v[164:167], v[196:199], v[118:121]
	v_mfma_f32_16x16x32_f16 v[110:113], v[168:171], v[196:199], v[110:113]
	v_mfma_f32_16x16x32_f16 v[102:105], v[164:167], v[204:207], v[102:105]
	v_mfma_f32_16x16x32_f16 v[94:97], v[168:171], v[204:207], v[94:97]
	v_mfma_f32_16x16x32_f16 v[86:89], v[164:167], v[216:219], v[86:89]
	v_mfma_f32_16x16x32_f16 v[78:81], v[168:171], v[216:219], v[78:81]
	v_mfma_f32_16x16x32_f16 v[66:69], v[164:167], v[220:223], v[66:69]
	v_mfma_f32_16x16x32_f16 v[58:61], v[168:171], v[220:223], v[58:61]
	v_mfma_f32_16x16x32_f16 v[118:121], v[172:175], v[208:211], v[118:121]
	v_mfma_f32_16x16x32_f16 v[110:113], v[176:179], v[208:211], v[110:113]
	v_mfma_f32_16x16x32_f16 v[102:105], v[172:175], v[212:215], v[102:105]
	v_mfma_f32_16x16x32_f16 v[94:97], v[176:179], v[212:215], v[94:97]
	v_mfma_f32_16x16x32_f16 v[86:89], v[172:175], v[224:227], v[86:89]
	v_mfma_f32_16x16x32_f16 v[78:81], v[176:179], v[224:227], v[78:81]
	v_mfma_f32_16x16x32_f16 v[66:69], v[172:175], v[228:231], v[66:69]
	v_mfma_f32_16x16x32_f16 v[58:61], v[176:179], v[228:231], v[58:61]
	s_setprio 0
	s_setprio 1
	v_mfma_f32_16x16x32_f16 v[126:129], v[180:183], v[196:199], v[126:129]
	v_mfma_f32_16x16x32_f16 v[122:125], v[184:187], v[196:199], v[122:125]
	v_mfma_f32_16x16x32_f16 v[114:117], v[180:183], v[204:207], v[114:117]
	v_mfma_f32_16x16x32_f16 v[106:109], v[184:187], v[204:207], v[106:109]
	v_mfma_f32_16x16x32_f16 v[98:101], v[180:183], v[216:219], v[98:101]
	v_mfma_f32_16x16x32_f16 v[90:93], v[184:187], v[216:219], v[90:93]
	v_mfma_f32_16x16x32_f16 v[82:85], v[180:183], v[220:223], v[82:85]
	v_mfma_f32_16x16x32_f16 v[74:77], v[184:187], v[220:223], v[74:77]
	v_mfma_f32_16x16x32_f16 v[126:129], v[188:191], v[208:211], v[126:129]
	v_mfma_f32_16x16x32_f16 v[122:125], v[192:195], v[208:211], v[122:125]
	v_mfma_f32_16x16x32_f16 v[114:117], v[188:191], v[212:215], v[114:117]
	v_mfma_f32_16x16x32_f16 v[106:109], v[192:195], v[212:215], v[106:109]
	v_mfma_f32_16x16x32_f16 v[98:101], v[188:191], v[224:227], v[98:101]
	v_mfma_f32_16x16x32_f16 v[90:93], v[192:195], v[224:227], v[90:93]
	v_mfma_f32_16x16x32_f16 v[82:85], v[188:191], v[228:231], v[82:85]
	v_mfma_f32_16x16x32_f16 v[74:77], v[192:195], v[228:231], v[74:77]
	s_setprio 0
	s_barrier
	s_mov_b32 m0, s35
	ds_read_b128 v[196:199], v161 offset:49152
	ds_read_b128 v[204:207], v161 offset:51200
	ds_read_b128 v[208:211], v162 offset:49152
	ds_read_b128 v[212:215], v162 offset:51200
	ds_read_b128 v[216:219], v161 offset:53248
	ds_read_b128 v[220:223], v161 offset:55296
	ds_read_b128 v[224:227], v162 offset:53248
	ds_read_b128 v[228:231], v162 offset:55296
	buffer_load_dwordx4 v154, s[8:11], s65 offen lds
	s_mov_b32 m0, s36
	s_add_i32 s62, s62, 0x80080
	buffer_load_dwordx4 v156, s[8:11], s65 offen lds
	s_mov_b32 m0, s39
	s_nop 0
	buffer_load_dwordx4 v154, s[8:11], s62 offen lds
	s_mov_b32 m0, s40
	s_nop 0
	buffer_load_dwordx4 v156, s[8:11], s62 offen lds
	s_mov_b32 m0, s37
	s_nop 0
	buffer_load_dwordx4 v153, s[48:51], s64 offen lds
	s_mov_b32 m0, s38
	s_nop 0
	buffer_load_dwordx4 v155, s[48:51], s64 offen lds
	s_waitcnt vmcnt(8)
	s_waitcnt lgkmcnt(0)
	s_barrier
	s_setprio 1
	s_waitcnt lgkmcnt(0)
	v_mfma_f32_16x16x32_f16 v[54:57], v[164:167], v[196:199], v[54:57]
	v_mfma_f32_16x16x32_f16 v[46:49], v[168:171], v[196:199], v[46:49]
	v_mfma_f32_16x16x32_f16 v[38:41], v[164:167], v[204:207], v[38:41]
	v_mfma_f32_16x16x32_f16 v[30:33], v[168:171], v[204:207], v[30:33]
	v_mfma_f32_16x16x32_f16 v[22:25], v[164:167], v[216:219], v[22:25]
	v_mfma_f32_16x16x32_f16 v[14:17], v[168:171], v[216:219], v[14:17]
	v_mfma_f32_16x16x32_f16 v[6:9], v[164:167], v[220:223], v[6:9]
	v_mfma_f32_16x16x32_f16 v[2:5], v[168:171], v[220:223], v[2:5]
	v_mfma_f32_16x16x32_f16 v[54:57], v[172:175], v[208:211], v[54:57]
	v_mfma_f32_16x16x32_f16 v[46:49], v[176:179], v[208:211], v[46:49]
	v_mfma_f32_16x16x32_f16 v[38:41], v[172:175], v[212:215], v[38:41]
	v_mfma_f32_16x16x32_f16 v[30:33], v[176:179], v[212:215], v[30:33]
	v_mfma_f32_16x16x32_f16 v[22:25], v[172:175], v[224:227], v[22:25]
	v_mfma_f32_16x16x32_f16 v[14:17], v[176:179], v[224:227], v[14:17]
	v_mfma_f32_16x16x32_f16 v[6:9], v[172:175], v[228:231], v[6:9]
	v_mfma_f32_16x16x32_f16 v[2:5], v[176:179], v[228:231], v[2:5]
	s_setprio 0
	s_setprio 1
	v_mfma_f32_16x16x32_f16 v[70:73], v[180:183], v[196:199], v[70:73]
	v_mfma_f32_16x16x32_f16 v[62:65], v[184:187], v[196:199], v[62:65]
	v_mfma_f32_16x16x32_f16 v[50:53], v[180:183], v[204:207], v[50:53]
	v_mfma_f32_16x16x32_f16 v[42:45], v[184:187], v[204:207], v[42:45]
	v_mfma_f32_16x16x32_f16 v[34:37], v[180:183], v[216:219], v[34:37]
	v_mfma_f32_16x16x32_f16 v[26:29], v[184:187], v[216:219], v[26:29]
	v_mfma_f32_16x16x32_f16 v[18:21], v[180:183], v[220:223], v[18:21]
	v_mfma_f32_16x16x32_f16 v[10:13], v[184:187], v[220:223], v[10:13]
	v_mfma_f32_16x16x32_f16 v[70:73], v[188:191], v[208:211], v[70:73]
	v_mfma_f32_16x16x32_f16 v[62:65], v[192:195], v[208:211], v[62:65]
	v_mfma_f32_16x16x32_f16 v[50:53], v[188:191], v[212:215], v[50:53]
	v_mfma_f32_16x16x32_f16 v[42:45], v[192:195], v[212:215], v[42:45]
	v_mfma_f32_16x16x32_f16 v[34:37], v[188:191], v[224:227], v[34:37]
	v_mfma_f32_16x16x32_f16 v[26:29], v[192:195], v[224:227], v[26:29]
	v_mfma_f32_16x16x32_f16 v[18:21], v[188:191], v[228:231], v[18:21]
	v_mfma_f32_16x16x32_f16 v[10:13], v[192:195], v[228:231], v[10:13]
	s_setprio 0
	s_barrier

.LBB0_147:
	s_waitcnt vmcnt(16)
	v_pk_mul_f32 v[128:129], v[120:121], v[128:129]
	v_alignbit_b32 v0, v131, v130, 24
	v_and_b32_e32 v147, 0xffffff, v130
	v_cvt_f32_u32_e32 v0, v0
	v_cvt_f32_u32_e32 v147, v147
	v_and_b32_e32 v148, 0xffffff, v144
	v_cvt_f32_u32_e32 v148, v148
	v_lshl_or_b32 v150, s53, 7, v160
	v_fmac_f32_e32 v0, 0x33800000, v147
	v_fmamk_f32 v0, v0, 0x3a000000, v200
	v_rsq_f32_e32 v167, v0
	v_alignbit_b32 v0, v133, v132, 24
	v_and_b32_e32 v147, 0xffffff, v132
	v_cvt_f32_u32_e32 v0, v0
	v_cvt_f32_u32_e32 v147, v147
	v_mul_f32_e32 v172, 0xbfb8aa3b, v167
	v_pk_mul_f32 v[174:175], v[118:119], v[172:173] op_sel_hi:[1,0]
	v_mul_f32_e32 v170, v167, v167
	v_fmac_f32_e32 v0, 0x33800000, v147
	v_fmamk_f32 v0, v0, 0x3a000000, v200
	v_rsq_f32_e32 v171, v0
	v_alignbit_b32 v0, v135, v134, 24
	v_and_b32_e32 v147, 0xffffff, v134
	v_cvt_f32_u32_e32 v0, v0
	v_cvt_f32_u32_e32 v147, v147
	v_exp_f32_e32 v174, v174
	v_exp_f32_e32 v175, v175
	v_pk_mul_f32 v[118:119], v[118:119], v[126:127]
	v_fmac_f32_e32 v0, 0x33800000, v147
	v_fmamk_f32 v0, v0, 0x3a000000, v200
	v_rsq_f32_e32 v166, v0
	v_alignbit_b32 v0, v137, v136, 24
	v_and_b32_e32 v147, 0xffffff, v136
	v_cvt_f32_u32_e32 v0, v0
	v_cvt_f32_u32_e32 v147, v147
	v_pk_add_f32 v[174:175], v[174:175], 1.0 op_sel_hi:[1,0]
	v_pk_mul_f32 v[120:121], v[120:121], v[172:173] op_sel_hi:[1,0]
	v_rcp_f32_e32 v174, v174
	v_fmac_f32_e32 v0, 0x33800000, v147
	v_fmamk_f32 v0, v0, 0x3a000000, v200
	v_rsq_f32_e32 v165, v0
	v_alignbit_b32 v0, v139, v138, 24
	v_and_b32_e32 v147, 0xffffff, v138
	v_rcp_f32_e32 v175, v175
	v_cvt_f32_u32_e32 v0, v0
	v_cvt_f32_u32_e32 v147, v147
	v_exp_f32_e32 v120, v120
	v_pk_mul_f32 v[126:127], v[170:171], v[174:175] op_sel_hi:[0,1]
	v_pk_mul_f32 v[118:119], v[118:119], v[126:127]
	v_fmac_f32_e32 v0, 0x33800000, v147
	v_pk_mul_f32 v[126:127], v[110:111], v[172:173] op_sel_hi:[1,0]
	v_fmamk_f32 v0, v0, 0x3a000000, v200
	v_exp_f32_e32 v126, v126
	v_exp_f32_e32 v127, v127
	v_rsq_f32_e32 v164, v0
	v_alignbit_b32 v0, v141, v140, 24
	v_and_b32_e32 v147, 0xffffff, v140
	v_cvt_f32_u32_e32 v0, v0
	v_cvt_f32_u32_e32 v147, v147
	v_pk_add_f32 v[126:127], v[126:127], 1.0 op_sel_hi:[1,0]
	v_pk_mul_f32 v[110:111], v[110:111], v[122:123]
	v_rcp_f32_e32 v126, v126
	v_rcp_f32_e32 v127, v127
	v_fmac_f32_e32 v0, 0x33800000, v147
	v_fmamk_f32 v0, v0, 0x3a000000, v200
	v_rsq_f32_e32 v163, v0
	v_alignbit_b32 v0, v143, v142, 24
	v_and_b32_e32 v147, 0xffffff, v142
	v_cvt_f32_u32_e32 v0, v0
	v_cvt_f32_u32_e32 v147, v147
	v_pk_mul_f32 v[122:123], v[170:171], v[126:127] op_sel_hi:[0,1]
	v_pk_mul_f32 v[122:123], v[110:111], v[122:123]
	v_pk_mul_f32 v[110:111], v[112:113], v[172:173] op_sel_hi:[1,0]
	v_exp_f32_e32 v121, v121
	v_exp_f32_e32 v110, v110
	v_exp_f32_e32 v111, v111
	v_fmac_f32_e32 v0, 0x33800000, v147
	v_fmamk_f32 v0, v0, 0x3a000000, v200
	v_rsq_f32_e32 v147, v0
	v_alignbit_b32 v0, v145, v144, 24
	v_pk_add_f32 v[120:121], v[120:121], 1.0 op_sel_hi:[1,0]
	v_pk_add_f32 v[110:111], v[110:111], 1.0 op_sel_hi:[1,0]
	v_cvt_f32_u32_e32 v0, v0
	v_rcp_f32_e32 v120, v120
	v_rcp_f32_e32 v121, v121
	v_rcp_f32_e32 v110, v110
	v_rcp_f32_e32 v111, v111
	v_fmac_f32_e32 v0, 0x33800000, v148
	v_ashrrev_i32_e32 v151, 31, v150
	v_mov_b64_e32 v[148:149], s[16:17]
	v_pk_mul_f32 v[120:121], v[170:171], v[120:121] op_sel_hi:[0,1]
	v_pk_mul_f32 v[124:125], v[112:113], v[124:125]
	v_pk_mul_f32 v[110:111], v[170:171], v[110:111] op_sel_hi:[0,1]
	v_mad_i64_i32 v[168:169], s[10:11], v146, s99, v[148:149]
	v_pk_mul_f32 v[120:121], v[128:129], v[120:121]
	v_pk_mul_f32 v[112:113], v[124:125], v[110:111]
	v_lshlrev_b64 v[110:111], 1, v[150:151]
	v_lshl_add_u64 v[124:125], v[168:169], 0, v[110:111]
	v_cvt_pk_bf16_f32 v118, v118, v119
	v_cvt_pk_bf16_f32 v119, v120, v121
	v_cvt_pk_bf16_f32 v120, v122, v123
	v_cvt_pk_bf16_f32 v121, v112, v113
	global_store_dwordx4 v[124:125], v[118:121], off
	v_pk_mul_f32 v[116:117], v[104:105], v[116:117]
	v_pk_mul_f32 v[108:109], v[96:97], v[108:109]
	v_mul_f32_e32 v120, 0xbfb8aa3b, v171
	v_pk_mul_f32 v[122:123], v[102:103], v[120:121] op_sel_hi:[1,0]
	v_mul_f32_e32 v118, v171, v171
	v_exp_f32_e32 v122, v122
	v_exp_f32_e32 v123, v123
	v_pk_mul_f32 v[102:103], v[102:103], v[114:115]
	v_pk_mul_f32 v[104:105], v[104:105], v[120:121] op_sel_hi:[1,0]
	v_or_b32_e32 v112, 16, v146
	v_pk_add_f32 v[122:123], v[122:123], 1.0 op_sel_hi:[1,0]
	v_exp_f32_e32 v104, v104
	v_rcp_f32_e32 v122, v122
	v_rcp_f32_e32 v123, v123
	v_exp_f32_e32 v105, v105
	v_mad_i64_i32 v[112:113], s[10:11], v112, s99, v[148:149]
	v_pk_mul_f32 v[114:115], v[118:119], v[122:123] op_sel_hi:[0,1]
	v_pk_mul_f32 v[102:103], v[102:103], v[114:115]
	v_pk_mul_f32 v[114:115], v[94:95], v[120:121] op_sel_hi:[1,0]
	v_pk_mul_f32 v[94:95], v[94:95], v[106:107]
	v_exp_f32_e32 v114, v114
	v_exp_f32_e32 v115, v115
	v_pk_add_f32 v[104:105], v[104:105], 1.0 op_sel_hi:[1,0]
	v_lshl_add_u64 v[112:113], v[112:113], 0, v[110:111]
	v_rcp_f32_e32 v104, v104
	v_pk_add_f32 v[114:115], v[114:115], 1.0 op_sel_hi:[1,0]
	v_rcp_f32_e32 v105, v105
	v_rcp_f32_e32 v114, v114
	v_rcp_f32_e32 v115, v115
	v_pk_mul_f32 v[100:101], v[88:89], v[100:101]
	v_pk_mul_f32 v[104:105], v[118:119], v[104:105] op_sel_hi:[0,1]
	v_pk_mul_f32 v[104:105], v[116:117], v[104:105]
	v_pk_mul_f32 v[106:107], v[118:119], v[114:115] op_sel_hi:[0,1]
	v_pk_mul_f32 v[106:107], v[94:95], v[106:107]
	v_pk_mul_f32 v[94:95], v[96:97], v[120:121] op_sel_hi:[1,0]
	v_pk_mul_f32 v[92:93], v[80:81], v[92:93]
	v_exp_f32_e32 v94, v94
	v_exp_f32_e32 v95, v95
	v_pk_mul_f32 v[84:85], v[68:69], v[84:85]
	v_pk_mul_f32 v[76:77], v[60:61], v[76:77]
	v_pk_mul_f32 v[72:73], v[56:57], v[72:73]
	v_pk_add_f32 v[94:95], v[94:95], 1.0 op_sel_hi:[1,0]
	v_pk_mul_f32 v[64:65], v[48:49], v[64:65]
	v_rcp_f32_e32 v94, v94
	v_rcp_f32_e32 v95, v95
	v_pk_mul_f32 v[52:53], v[40:41], v[52:53]
	v_pk_mul_f32 v[44:45], v[32:33], v[44:45]
	v_pk_mul_f32 v[36:37], v[24:25], v[36:37]
	v_pk_mul_f32 v[94:95], v[118:119], v[94:95] op_sel_hi:[0,1]
	v_pk_mul_f32 v[108:109], v[108:109], v[94:95]
	v_cvt_pk_bf16_f32 v94, v102, v103
	v_mul_f32_e32 v102, 0xbfb8aa3b, v166
	v_cvt_pk_bf16_f32 v95, v104, v105
	v_pk_mul_f32 v[104:105], v[86:87], v[102:103] op_sel_hi:[1,0]
	v_cvt_pk_bf16_f32 v96, v106, v107
	v_cvt_pk_bf16_f32 v97, v108, v109
	global_store_dwordx4 v[112:113], v[94:97], off
	v_exp_f32_e32 v104, v104
	v_exp_f32_e32 v105, v105
	v_mul_f32_e32 v96, v166, v166
	v_pk_mul_f32 v[86:87], v[86:87], v[98:99]
	v_pk_mul_f32 v[88:89], v[88:89], v[102:103] op_sel_hi:[1,0]
	v_pk_add_f32 v[104:105], v[104:105], 1.0 op_sel_hi:[1,0]
	v_exp_f32_e32 v88, v88
	v_rcp_f32_e32 v104, v104
	v_rcp_f32_e32 v105, v105
	v_exp_f32_e32 v89, v89
	v_or_b32_e32 v94, 32, v146
	v_mad_i64_i32 v[94:95], s[10:11], v94, s99, v[148:149]
	v_pk_mul_f32 v[98:99], v[96:97], v[104:105] op_sel_hi:[0,1]
	v_pk_mul_f32 v[86:87], v[86:87], v[98:99]
	v_pk_mul_f32 v[98:99], v[78:79], v[102:103] op_sel_hi:[1,0]
	v_pk_mul_f32 v[78:79], v[78:79], v[90:91]
	v_exp_f32_e32 v98, v98
	v_exp_f32_e32 v99, v99
	v_pk_add_f32 v[88:89], v[88:89], 1.0 op_sel_hi:[1,0]
	v_lshl_add_u64 v[94:95], v[94:95], 0, v[110:111]
	v_rcp_f32_e32 v88, v88
	v_pk_add_f32 v[98:99], v[98:99], 1.0 op_sel_hi:[1,0]
	v_rcp_f32_e32 v89, v89
	v_rcp_f32_e32 v98, v98
	v_rcp_f32_e32 v99, v99
	v_fmamk_f32 v0, v0, 0x3a000000, v200
	v_pk_mul_f32 v[88:89], v[96:97], v[88:89] op_sel_hi:[0,1]
	v_pk_mul_f32 v[88:89], v[100:101], v[88:89]
	v_pk_mul_f32 v[90:91], v[96:97], v[98:99] op_sel_hi:[0,1]
	v_pk_mul_f32 v[90:91], v[78:79], v[90:91]
	v_pk_mul_f32 v[78:79], v[80:81], v[102:103] op_sel_hi:[1,0]
	v_rsq_f32_e32 v0, v0
	v_exp_f32_e32 v78, v78
	v_exp_f32_e32 v79, v79
	v_pk_mul_f32 v[28:29], v[16:17], v[28:29]
	v_pk_mul_f32 v[20:21], v[8:9], v[20:21]
	v_pk_mul_f32 v[12:13], v[4:5], v[12:13]
	v_pk_add_f32 v[78:79], v[78:79], 1.0 op_sel_hi:[1,0]
	s_andn2_b64 vcc, exec, s[4:5]
	v_rcp_f32_e32 v78, v78
	v_rcp_f32_e32 v79, v79
	s_nop 0
	v_pk_mul_f32 v[78:79], v[96:97], v[78:79] op_sel_hi:[0,1]
	v_pk_mul_f32 v[92:93], v[92:93], v[78:79]
	v_cvt_pk_bf16_f32 v78, v86, v87
	v_mul_f32_e32 v86, 0xbfb8aa3b, v165
	v_cvt_pk_bf16_f32 v79, v88, v89
	v_pk_mul_f32 v[88:89], v[66:67], v[86:87] op_sel_hi:[1,0]
	v_cvt_pk_bf16_f32 v80, v90, v91
	v_cvt_pk_bf16_f32 v81, v92, v93
	global_store_dwordx4 v[94:95], v[78:81], off
	v_exp_f32_e32 v88, v88
	v_exp_f32_e32 v89, v89
	v_mul_f32_e32 v80, v165, v165
	v_pk_mul_f32 v[66:67], v[66:67], v[82:83]
	v_pk_mul_f32 v[68:69], v[68:69], v[86:87] op_sel_hi:[1,0]
	v_pk_add_f32 v[88:89], v[88:89], 1.0 op_sel_hi:[1,0]
	v_exp_f32_e32 v68, v68
	v_rcp_f32_e32 v88, v88
	v_rcp_f32_e32 v89, v89
	v_exp_f32_e32 v69, v69
	v_or_b32_e32 v78, 48, v146
	v_mad_i64_i32 v[78:79], s[10:11], v78, s99, v[148:149]
	v_pk_mul_f32 v[82:83], v[80:81], v[88:89] op_sel_hi:[0,1]
	v_pk_mul_f32 v[66:67], v[66:67], v[82:83]
	v_pk_mul_f32 v[82:83], v[58:59], v[86:87] op_sel_hi:[1,0]
	v_pk_mul_f32 v[58:59], v[58:59], v[74:75]
	v_exp_f32_e32 v82, v82
	v_exp_f32_e32 v83, v83
	v_pk_add_f32 v[68:69], v[68:69], 1.0 op_sel_hi:[1,0]
	v_lshl_add_u64 v[78:79], v[78:79], 0, v[110:111]
	v_rcp_f32_e32 v68, v68
	v_pk_add_f32 v[82:83], v[82:83], 1.0 op_sel_hi:[1,0]
	v_rcp_f32_e32 v69, v69
	v_rcp_f32_e32 v82, v82
	v_rcp_f32_e32 v83, v83
	v_pk_mul_f32 v[68:69], v[80:81], v[68:69] op_sel_hi:[0,1]
	v_pk_mul_f32 v[68:69], v[84:85], v[68:69]
	v_pk_mul_f32 v[74:75], v[80:81], v[82:83] op_sel_hi:[0,1]
	v_pk_mul_f32 v[74:75], v[58:59], v[74:75]
	v_pk_mul_f32 v[58:59], v[60:61], v[86:87] op_sel_hi:[1,0]
	s_nop 0
	v_exp_f32_e32 v58, v58
	v_exp_f32_e32 v59, v59
	s_nop 0
	v_pk_add_f32 v[58:59], v[58:59], 1.0 op_sel_hi:[1,0]
	s_nop 0
	v_rcp_f32_e32 v58, v58
	v_rcp_f32_e32 v59, v59
	s_nop 0
	v_pk_mul_f32 v[58:59], v[80:81], v[58:59] op_sel_hi:[0,1]
	v_pk_mul_f32 v[76:77], v[76:77], v[58:59]
	v_cvt_pk_bf16_f32 v58, v66, v67
	v_mul_f32_e32 v66, 0xbfb8aa3b, v164
	v_cvt_pk_bf16_f32 v59, v68, v69
	v_pk_mul_f32 v[68:69], v[54:55], v[66:67] op_sel_hi:[1,0]
	v_cvt_pk_bf16_f32 v60, v74, v75
	v_cvt_pk_bf16_f32 v61, v76, v77
	global_store_dwordx4 v[78:79], v[58:61], off
	v_exp_f32_e32 v68, v68
	v_exp_f32_e32 v69, v69
	v_mul_f32_e32 v60, v164, v164
	v_pk_mul_f32 v[54:55], v[54:55], v[70:71]
	v_pk_mul_f32 v[56:57], v[56:57], v[66:67] op_sel_hi:[1,0]
	v_pk_add_f32 v[68:69], v[68:69], 1.0 op_sel_hi:[1,0]
	v_exp_f32_e32 v56, v56
	v_rcp_f32_e32 v68, v68
	v_rcp_f32_e32 v69, v69
	v_exp_f32_e32 v57, v57
	v_add_u32_e32 v58, 0x80, v146
	v_mad_i64_i32 v[58:59], s[10:11], v58, s99, v[148:149]
	v_pk_mul_f32 v[68:69], v[60:61], v[68:69] op_sel_hi:[0,1]
	v_pk_mul_f32 v[54:55], v[54:55], v[68:69]
	v_pk_mul_f32 v[68:69], v[46:47], v[66:67] op_sel_hi:[1,0]
	v_pk_mul_f32 v[46:47], v[46:47], v[62:63]
	v_exp_f32_e32 v68, v68
	v_exp_f32_e32 v69, v69
	v_pk_add_f32 v[56:57], v[56:57], 1.0 op_sel_hi:[1,0]
	v_lshl_add_u64 v[58:59], v[58:59], 0, v[110:111]
	v_rcp_f32_e32 v56, v56
	v_pk_add_f32 v[68:69], v[68:69], 1.0 op_sel_hi:[1,0]
	v_rcp_f32_e32 v57, v57
	v_rcp_f32_e32 v68, v68
	v_rcp_f32_e32 v69, v69
	v_pk_mul_f32 v[56:57], v[60:61], v[56:57] op_sel_hi:[0,1]
	v_pk_mul_f32 v[56:57], v[72:73], v[56:57]
	v_pk_mul_f32 v[62:63], v[60:61], v[68:69] op_sel_hi:[0,1]
	v_pk_mul_f32 v[62:63], v[46:47], v[62:63]
	v_pk_mul_f32 v[46:47], v[48:49], v[66:67] op_sel_hi:[1,0]
	s_nop 0
	v_exp_f32_e32 v46, v46
	v_exp_f32_e32 v47, v47
	s_nop 0
	v_pk_add_f32 v[46:47], v[46:47], 1.0 op_sel_hi:[1,0]
	s_nop 0
	v_rcp_f32_e32 v46, v46
	v_rcp_f32_e32 v47, v47
	s_nop 0
	v_pk_mul_f32 v[46:47], v[60:61], v[46:47] op_sel_hi:[0,1]
	v_pk_mul_f32 v[60:61], v[64:65], v[46:47]
	v_cvt_pk_bf16_f32 v46, v54, v55
	v_mul_f32_e32 v54, 0xbfb8aa3b, v163
	v_cvt_pk_bf16_f32 v47, v56, v57
	v_pk_mul_f32 v[56:57], v[38:39], v[54:55] op_sel_hi:[1,0]
	v_cvt_pk_bf16_f32 v48, v62, v63
	v_cvt_pk_bf16_f32 v49, v60, v61
	global_store_dwordx4 v[58:59], v[46:49], off
	v_exp_f32_e32 v56, v56
	v_exp_f32_e32 v57, v57
	v_mul_f32_e32 v48, v163, v163
	v_pk_mul_f32 v[38:39], v[38:39], v[50:51]
	v_pk_mul_f32 v[40:41], v[40:41], v[54:55] op_sel_hi:[1,0]
	v_pk_add_f32 v[56:57], v[56:57], 1.0 op_sel_hi:[1,0]
	v_exp_f32_e32 v40, v40
	v_rcp_f32_e32 v56, v56
	v_rcp_f32_e32 v57, v57
	v_exp_f32_e32 v41, v41
	v_add_u32_e32 v46, 0x90, v146
	v_mad_i64_i32 v[46:47], s[10:11], v46, s99, v[148:149]
	v_pk_mul_f32 v[50:51], v[48:49], v[56:57] op_sel_hi:[0,1]
	v_pk_mul_f32 v[38:39], v[38:39], v[50:51]
	v_pk_mul_f32 v[50:51], v[30:31], v[54:55] op_sel_hi:[1,0]
	v_pk_mul_f32 v[30:31], v[30:31], v[42:43]
	v_exp_f32_e32 v50, v50
	v_exp_f32_e32 v51, v51
	v_pk_add_f32 v[40:41], v[40:41], 1.0 op_sel_hi:[1,0]
	v_lshl_add_u64 v[46:47], v[46:47], 0, v[110:111]
	v_rcp_f32_e32 v40, v40
	v_pk_add_f32 v[50:51], v[50:51], 1.0 op_sel_hi:[1,0]
	v_rcp_f32_e32 v41, v41
	v_rcp_f32_e32 v50, v50
	v_rcp_f32_e32 v51, v51
	v_pk_mul_f32 v[40:41], v[48:49], v[40:41] op_sel_hi:[0,1]
	v_pk_mul_f32 v[40:41], v[52:53], v[40:41]
	v_pk_mul_f32 v[42:43], v[48:49], v[50:51] op_sel_hi:[0,1]
	v_pk_mul_f32 v[42:43], v[30:31], v[42:43]
	v_pk_mul_f32 v[30:31], v[32:33], v[54:55] op_sel_hi:[1,0]
	s_nop 0
	v_exp_f32_e32 v30, v30
	v_exp_f32_e32 v31, v31
	s_nop 0
	v_pk_add_f32 v[30:31], v[30:31], 1.0 op_sel_hi:[1,0]
	s_nop 0
	v_rcp_f32_e32 v30, v30
	v_rcp_f32_e32 v31, v31
	s_nop 0
	v_pk_mul_f32 v[30:31], v[48:49], v[30:31] op_sel_hi:[0,1]
	v_pk_mul_f32 v[44:45], v[44:45], v[30:31]
	v_cvt_pk_bf16_f32 v30, v38, v39
	v_mul_f32_e32 v38, 0xbfb8aa3b, v147
	v_cvt_pk_bf16_f32 v31, v40, v41
	v_pk_mul_f32 v[40:41], v[22:23], v[38:39] op_sel_hi:[1,0]
	v_cvt_pk_bf16_f32 v32, v42, v43
	v_cvt_pk_bf16_f32 v33, v44, v45
	global_store_dwordx4 v[46:47], v[30:33], off
	v_exp_f32_e32 v40, v40
	v_exp_f32_e32 v41, v41
	v_mul_f32_e32 v32, v147, v147
	v_pk_mul_f32 v[22:23], v[22:23], v[34:35]
	v_pk_mul_f32 v[24:25], v[24:25], v[38:39] op_sel_hi:[1,0]
	v_pk_add_f32 v[40:41], v[40:41], 1.0 op_sel_hi:[1,0]
	v_exp_f32_e32 v24, v24
	v_rcp_f32_e32 v40, v40
	v_rcp_f32_e32 v41, v41
	v_exp_f32_e32 v25, v25
	v_add_u32_e32 v30, 0xa0, v146
	v_mad_i64_i32 v[30:31], s[10:11], v30, s99, v[148:149]
	v_pk_mul_f32 v[34:35], v[32:33], v[40:41] op_sel_hi:[0,1]
	v_pk_mul_f32 v[22:23], v[22:23], v[34:35]
	v_pk_mul_f32 v[34:35], v[14:15], v[38:39] op_sel_hi:[1,0]
	v_pk_mul_f32 v[14:15], v[14:15], v[26:27]
	v_exp_f32_e32 v34, v34
	v_exp_f32_e32 v35, v35
	v_pk_add_f32 v[24:25], v[24:25], 1.0 op_sel_hi:[1,0]
	v_lshl_add_u64 v[30:31], v[30:31], 0, v[110:111]
	v_rcp_f32_e32 v24, v24
	v_pk_add_f32 v[34:35], v[34:35], 1.0 op_sel_hi:[1,0]
	v_rcp_f32_e32 v25, v25
	v_rcp_f32_e32 v34, v34
	v_rcp_f32_e32 v35, v35
	v_pk_mul_f32 v[24:25], v[32:33], v[24:25] op_sel_hi:[0,1]
	v_pk_mul_f32 v[24:25], v[36:37], v[24:25]
	v_pk_mul_f32 v[26:27], v[32:33], v[34:35] op_sel_hi:[0,1]
	v_pk_mul_f32 v[26:27], v[14:15], v[26:27]
	v_pk_mul_f32 v[14:15], v[16:17], v[38:39] op_sel_hi:[1,0]
	s_nop 0
	v_exp_f32_e32 v14, v14
	v_exp_f32_e32 v15, v15
	s_nop 0
	v_pk_add_f32 v[14:15], v[14:15], 1.0 op_sel_hi:[1,0]
	s_nop 0
	v_rcp_f32_e32 v14, v14
	v_rcp_f32_e32 v15, v15
	s_nop 0
	v_pk_mul_f32 v[14:15], v[32:33], v[14:15] op_sel_hi:[0,1]
	v_pk_mul_f32 v[28:29], v[28:29], v[14:15]
	v_cvt_pk_bf16_f32 v14, v22, v23
	v_cvt_pk_bf16_f32 v15, v24, v25
	v_cvt_pk_bf16_f32 v16, v26, v27
	s_nop 0
	v_cvt_pk_bf16_f32 v17, v28, v29
	global_store_dwordx4 v[30:31], v[14:17], off
	s_nop 1
	v_mul_f32_e32 v16, v0, v0
	v_mul_f32_e32 v0, 0xbfb8aa3b, v0
	v_pk_mul_f32 v[22:23], v[6:7], v[0:1] op_sel_hi:[1,0]
	v_pk_mul_f32 v[6:7], v[6:7], v[18:19]
	v_exp_f32_e32 v22, v22
	v_exp_f32_e32 v23, v23
	v_pk_mul_f32 v[8:9], v[8:9], v[0:1] op_sel_hi:[1,0]
	v_add_u32_e32 v14, 0xb0, v146
	v_exp_f32_e32 v8, v8
	v_pk_add_f32 v[22:23], v[22:23], 1.0 op_sel_hi:[1,0]
	v_exp_f32_e32 v9, v9
	v_rcp_f32_e32 v22, v22
	v_rcp_f32_e32 v23, v23
	v_mad_i64_i32 v[14:15], s[10:11], v14, s99, v[148:149]
	v_pk_add_f32 v[8:9], v[8:9], 1.0 op_sel_hi:[1,0]
	v_pk_mul_f32 v[18:19], v[16:17], v[22:23] op_sel_hi:[0,1]
	v_pk_mul_f32 v[6:7], v[6:7], v[18:19]
	v_pk_mul_f32 v[18:19], v[2:3], v[0:1] op_sel_hi:[1,0]
	v_pk_mul_f32 v[2:3], v[2:3], v[10:11]
	v_exp_f32_e32 v18, v18
	v_exp_f32_e32 v19, v19
	v_rcp_f32_e32 v8, v8
	v_rcp_f32_e32 v9, v9
	v_lshl_add_u64 v[14:15], v[14:15], 0, v[110:111]
	v_pk_add_f32 v[18:19], v[18:19], 1.0 op_sel_hi:[1,0]
	s_mov_b64 s[10:11], -1
	v_rcp_f32_e32 v18, v18
	v_rcp_f32_e32 v19, v19
	v_pk_mul_f32 v[8:9], v[16:17], v[8:9] op_sel_hi:[0,1]
	v_pk_mul_f32 v[8:9], v[20:21], v[8:9]
	v_pk_mul_f32 v[10:11], v[16:17], v[18:19] op_sel_hi:[0,1]
	v_pk_mul_f32 v[10:11], v[2:3], v[10:11]
	v_pk_mul_f32 v[2:3], v[4:5], v[0:1] op_sel_hi:[1,0]
	s_nop 0
	v_exp_f32_e32 v2, v2
	v_exp_f32_e32 v3, v3
	s_nop 0
	v_pk_add_f32 v[2:3], v[2:3], 1.0 op_sel_hi:[1,0]
	s_nop 0
	v_rcp_f32_e32 v2, v2
	v_rcp_f32_e32 v3, v3
	s_nop 0
	v_pk_mul_f32 v[2:3], v[16:17], v[2:3] op_sel_hi:[0,1]
	v_pk_mul_f32 v[12:13], v[12:13], v[2:3]
	v_cvt_pk_bf16_f32 v2, v6, v7
	v_cvt_pk_bf16_f32 v3, v8, v9
	v_cvt_pk_bf16_f32 v4, v10, v11
	s_nop 0
	v_cvt_pk_bf16_f32 v5, v12, v13
	global_store_dwordx4 v[14:15], v[2:5], off
	s_cbranch_vccnz .LBB0_138
	s_nop 0
	v_mov_b32_e32 v2, v1
	v_mov_b32_e32 v3, v1
	v_mov_b32_e32 v0, v1
	v_mov_b64_e32 v[12:13], v[2:3]
	v_mov_b64_e32 v[10:11], v[0:1]
	s_andn2_b64 vcc, exec, s[14:15]
	s_cbranch_vccnz .LBB0_137
	s_barrier
	s_branch .LBB0_137

.LBB0_152:
	s_andn2_b64 vcc, exec, s[4:5]
	s_cbranch_vccnz .LBB0_171
	s_cmp_ge_i32 s25, s74
	v_readfirstlane_b32 s4, v152
	s_cbranch_scc1 .LBB0_171
	v_readlane_b32 s2, v255, 40
	s_add_u32 s2, s12, s2
	s_addc_u32 s3, s13, 0
	s_add_u32 s5, s2, 0x21200000
	s_addc_u32 s9, s3, 0
	v_readlane_b32 s2, v255, 39
	s_add_u32 s2, s12, s2
	s_addc_u32 s3, s13, 0
	s_add_u32 s8, s2, 0x24600000
	s_addc_u32 s10, s3, 0
	v_readlane_b32 s2, v255, 31
	v_readlane_b32 s3, v255, 32
	s_and_b64 s[2:3], s[2:3], exec
	s_cselect_b32 s8, s5, s8
	s_cselect_b32 s9, s9, s10
	s_lshl_b64 s[2:3], s[56:57], 12
	s_add_u32 s48, s0, s2
	s_addc_u32 s0, s1, s3
	s_ashr_i32 s18, s4, 6
	v_and_b32_e32 v130, 63, v152
	s_lshl_b32 s1, s18, 3
	v_bfe_u32 v0, v152, 3, 3
	s_lshl_b32 s2, s18, 1
	v_bfe_u32 v2, v130, 3, 2
	v_and_or_b32 v4, s2, 4, v2
	v_or_b32_e32 v2, s1, v0
	v_lshrrev_b32_e32 v3, 1, v2
	s_and_b32 s49, s0, 0xffff
	s_ashr_i32 s0, s25, 31
	v_xor_b32_e32 v3, v3, v152
	v_lshlrev_b32_e32 v5, 1, v2
	s_lshr_b32 s3, s0, 29
	v_lshlrev_b32_e32 v3, 4, v3
	s_and_b32 s2, s1, 0xfffe0
	v_and_b32_e32 v5, 24, v5
	s_add_i32 s3, s25, s3
	v_and_b32_e32 v3, 0x70, v3
	v_or3_b32 v5, s2, v5, v4
	s_add_i32 s1, s1, 64
	s_ashr_i32 s10, s3, 3
	s_and_b32 s3, s3, -8
	s_ashr_i32 s5, s4, 8
	v_lshl_or_b32 v153, v5, 12, v3
	v_or_b32_e32 v5, s1, v0
	s_and_b32 s2, s1, 0xfffe0
	s_and_b32 s9, s9, 0xffff
	s_lshl_b32 s1, s18, 10
	s_sub_i32 s3, s25, s3
	s_cmp_lt_i32 s3, 0
	v_readlane_b32 s11, v255, 35
	v_readlane_b32 s14, v255, 36
	s_cselect_b32 s11, s14, s11
	s_mul_i32 s3, s3, s11
	s_add_i32 s3, s3, s10
	s_ashr_i32 s10, s3, 31
	v_readlane_b32 s11, v255, 43
	s_xor_b32 s10, s10, s11
	s_abs_i32 s11, s3
	v_readlane_b32 s14, v255, 44
	s_mul_hi_u32 s14, s11, s14
	s_mul_i32 s15, s14, s79
	s_sub_i32 s11, s11, s15
	s_add_i32 s15, s14, 1
	s_sub_i32 s16, s11, s79
	s_cmp_ge_u32 s11, s79
	s_cselect_b32 s14, s15, s14
	s_cselect_b32 s11, s16, s11
	s_add_i32 s15, s14, 1
	s_cmp_ge_u32 s11, s79
	s_cselect_b32 s11, s15, s14
	s_xor_b32 s11, s11, s10
	v_lshrrev_b32_e32 v0, 1, v5
	s_sub_i32 s14, s11, s10
	v_xor_b32_e32 v0, v0, v152
	s_lshl_b32 s15, s14, 2
	v_lshlrev_b32_e32 v0, 4, v0
	s_sub_i32 s10, 16, s15
	v_lshl_or_b32 v151, v2, 12, v3
	v_and_b32_e32 v6, 0x70, v0
	v_lshlrev_b32_e32 v0, 1, v5
	v_mov_b32_e32 v2, v1
	v_mov_b32_e32 v3, v1
	s_min_i32 s16, s10, 4
	v_and_b32_e32 v7, 24, v0
	v_mov_b32_e32 v0, v1
	v_mov_b64_e32 v[52:53], v[2:3]
	s_abs_i32 s17, s16
	v_mov_b64_e32 v[50:51], v[0:1]
	v_cvt_f32_u32_e32 v0, s17
	v_or3_b32 v2, s2, v7, v4
	s_nop 0
	v_rcp_iflag_f32_e32 v0, v0
	v_readlane_b32 s19, v255, 42
	s_nop 0
	v_mul_f32_e32 v0, 0x4f7ffffe, v0
	v_cvt_u32_f32_e32 v0, v0
	s_nop 0
	s_sub_i32 s20, 0, s17
	v_readfirstlane_b32 s2, v0
	s_nop 0
	s_mul_i32 s14, s14, s19
	s_mul_i32 s20, s20, s2
	s_nop 0
	s_sub_i32 s3, s3, s14
	s_mul_hi_u32 s20, s2, s20
	s_nop 0
	s_abs_i32 s19, s3
	s_add_i32 s2, s2, s20
	s_nop 0
	s_mul_hi_u32 s2, s19, s2
	s_mul_i32 s20, s2, s17
	s_nop 0
	s_xor_b32 s14, s3, s16
	s_sub_i32 s19, s19, s20
	s_nop 0
	s_ashr_i32 s14, s14, 31
	s_add_i32 s20, s2, 1
	s_nop 0
	s_sub_i32 s21, s19, s17
	s_cmp_ge_u32 s19, s17
	s_nop 0
	s_cselect_b32 s2, s20, s2
	s_cselect_b32 s19, s21, s19
	s_nop 0
	s_add_i32 s20, s2, 1
	v_lshl_or_b32 v155, v5, 12, v6
	s_nop 0
	v_lshl_or_b32 v156, v2, 12, v6
	s_cmp_ge_u32 s19, s17
	s_nop 0
	s_cselect_b32 s2, s20, s2
	s_xor_b32 s2, s2, s14
	s_nop 0
	s_sub_i32 s45, s2, s14
	s_mul_i32 s2, s45, s16
	s_nop 0
	s_sub_i32 s2, s3, s2
	s_add_i32 s1, s1, 0
	s_nop 0
	s_add_i32 s52, s2, s15
	s_add_i32 s2, s1, 0x10000
	s_nop 0
	s_mov_b32 s10, s50
	s_mov_b32 s11, s51
	s_nop 0
	s_lshl_b32 s53, s45, 20
	s_mov_b32 m0, s2
	s_nop 0
	s_add_i32 s3, s1, 0x12000
	s_add_i32 s20, s1, 0x14000
	s_nop 0
	s_or_b32 s14, s53, 0x80000
	s_add_i32 s21, s1, 0x16000
	s_nop 0
	s_lshl_b32 s54, s52, 20
	s_add_i32 s26, s1, 0x2000
	s_nop 0
	s_add_i32 s27, s1, 0x4000
	s_add_i32 s28, s1, 0x6000
	s_nop 0
	s_nop 0
	s_nop 0
	s_nop 0
	s_nop 0
	s_nop 0
	s_nop 0
	s_nop 0
	s_nop 0
	s_nop 0
	s_nop 0
	s_nop 0
	s_nop 0
	s_nop 0
	s_nop 0
	buffer_load_dwordx4 v153, s[8:11], s53 offen lds
	s_mov_b32 m0, s3
	s_nop 0
	buffer_load_dwordx4 v156, s[8:11], s53 offen lds
	s_mov_b32 m0, s20
	s_nop 0
	buffer_load_dwordx4 v153, s[8:11], s14 offen lds
	s_mov_b32 m0, s21
	s_nop 0
	buffer_load_dwordx4 v156, s[8:11], s14 offen lds
	s_mov_b32 m0, s1
	s_or_b32 s10, s54, 0x80000
	buffer_load_dwordx4 v151, s[48:51], s54 offen lds
	s_mov_b32 m0, s26
	s_cmp_eq_u32 s5, 1
	buffer_load_dwordx4 v155, s[48:51], s54 offen lds
	s_mov_b32 m0, s27
	s_cselect_b64 s[14:15], -1, 0
	buffer_load_dwordx4 v151, s[48:51], s10 offen lds
	s_mov_b32 m0, s28
	s_cmp_lg_u32 s5, 1
	buffer_load_dwordx4 v155, s[48:51], s10 offen lds
	s_cbranch_scc1 .LBB0_156
	s_barrier

.Lc0b_first:
	s_add_i32 s55, s52, 0xfff80080
	s_and_b64 s[10:11], s[10:11], exec
	s_cselect_b32 s60, s46, s55
	s_cselect_b32 s55, s47, s53
	s_add_i32 s10, 0, 0x10000
	v_add_u32_e32 v0, s10, v157
	v_add_u32_e32 v147, s10, v158
	s_add_i32 s10, 0, 0x14000
	ds_read_b128 v[164:167], v0
	ds_read_b128 v[168:171], v0 offset:2048
	ds_read_b128 v[172:175], v147
	ds_read_b128 v[176:179], v147 offset:2048
	v_add_u32_e32 v0, s10, v157
	v_add_u32_e32 v147, s10, v158
	ds_read_b128 v[180:183], v0
	ds_read_b128 v[184:187], v0 offset:2048
	ds_read_b128 v[188:191], v147
	ds_read_b128 v[192:195], v147 offset:2048
	s_or_b32 s56, s60, 0x80
	s_or_b32 s58, s55, 0x80
	s_mov_b32 m0, s37
	ds_read_b128 v[196:199], v161
	ds_read_b128 v[204:207], v161 offset:2048
	ds_read_b128 v[208:211], v162
	ds_read_b128 v[212:215], v162 offset:2048
	ds_read_b128 v[216:219], v161 offset:4096
	ds_read_b128 v[220:223], v161 offset:6144
	ds_read_b128 v[224:227], v162 offset:4096
	ds_read_b128 v[228:231], v162 offset:6144
	buffer_load_dwordx4 v151, s[48:51], s52 offen lds
	s_mov_b32 m0, s38
	s_nop 0
	buffer_load_dwordx4 v155, s[48:51], s52 offen lds
	s_waitcnt vmcnt(8)
	s_waitcnt lgkmcnt(0)
	s_barrier
	s_setprio 1
	s_waitcnt lgkmcnt(0)
	v_mfma_f32_16x16x32_f16 v[94:97], v[164:167], v[196:199], 0
	v_mfma_f32_16x16x32_f16 v[98:101], v[168:171], v[196:199], 0
	v_mfma_f32_16x16x32_f16 v[62:65], v[164:167], v[204:207], 0
	v_mfma_f32_16x16x32_f16 v[74:77], v[168:171], v[204:207], 0
	v_mfma_f32_16x16x32_f16 v[34:37], v[164:167], v[216:219], 0
	v_mfma_f32_16x16x32_f16 v[42:45], v[168:171], v[216:219], 0
	v_mfma_f32_16x16x32_f16 v[14:17], v[164:167], v[220:223], 0
	v_mfma_f32_16x16x32_f16 v[22:25], v[168:171], v[220:223], 0
	v_mfma_f32_16x16x32_f16 v[94:97], v[172:175], v[208:211], v[94:97]
	v_mfma_f32_16x16x32_f16 v[98:101], v[176:179], v[208:211], v[98:101]
	v_mfma_f32_16x16x32_f16 v[62:65], v[172:175], v[212:215], v[62:65]
	v_mfma_f32_16x16x32_f16 v[74:77], v[176:179], v[212:215], v[74:77]
	v_mfma_f32_16x16x32_f16 v[34:37], v[172:175], v[224:227], v[34:37]
	v_mfma_f32_16x16x32_f16 v[42:45], v[176:179], v[224:227], v[42:45]
	v_mfma_f32_16x16x32_f16 v[14:17], v[172:175], v[228:231], v[14:17]
	v_mfma_f32_16x16x32_f16 v[22:25], v[176:179], v[228:231], v[22:25]
	s_setprio 0
	s_setprio 1
	v_mfma_f32_16x16x32_f16 v[122:125], v[180:183], v[196:199], 0
	v_mfma_f32_16x16x32_f16 v[126:129], v[184:187], v[196:199], 0
	v_mfma_f32_16x16x32_f16 v[110:113], v[180:183], v[204:207], 0
	v_mfma_f32_16x16x32_f16 v[118:121], v[184:187], v[204:207], 0
	v_mfma_f32_16x16x32_f16 v[86:89], v[180:183], v[216:219], 0
	v_mfma_f32_16x16x32_f16 v[102:105], v[184:187], v[216:219], 0
	v_mfma_f32_16x16x32_f16 v[70:73], v[180:183], v[220:223], 0
	v_mfma_f32_16x16x32_f16 v[78:81], v[184:187], v[220:223], 0
	v_mfma_f32_16x16x32_f16 v[122:125], v[188:191], v[208:211], v[122:125]
	v_mfma_f32_16x16x32_f16 v[126:129], v[192:195], v[208:211], v[126:129]
	v_mfma_f32_16x16x32_f16 v[110:113], v[188:191], v[212:215], v[110:113]
	v_mfma_f32_16x16x32_f16 v[118:121], v[192:195], v[212:215], v[118:121]
	v_mfma_f32_16x16x32_f16 v[86:89], v[188:191], v[224:227], v[86:89]
	v_mfma_f32_16x16x32_f16 v[102:105], v[192:195], v[224:227], v[102:105]
	v_mfma_f32_16x16x32_f16 v[70:73], v[188:191], v[228:231], v[70:73]
	v_mfma_f32_16x16x32_f16 v[78:81], v[192:195], v[228:231], v[78:81]
	s_setprio 0
	s_barrier
	s_mov_b32 m0, s2
	s_mov_b32 s10, s50
	s_mov_b32 s11, s51
	ds_read_b128 v[196:199], v161 offset:16384
	ds_read_b128 v[204:207], v161 offset:18432
	ds_read_b128 v[208:211], v162 offset:16384
	ds_read_b128 v[212:215], v162 offset:18432
	ds_read_b128 v[216:219], v161 offset:20480
	ds_read_b128 v[220:223], v161 offset:22528
	ds_read_b128 v[224:227], v162 offset:20480
	ds_read_b128 v[228:231], v162 offset:22528
	buffer_load_dwordx4 v153, s[8:11], s55 offen lds
	s_mov_b32 m0, s3
	s_add_i32 s61, s55, 0x80000
	buffer_load_dwordx4 v156, s[8:11], s55 offen lds
	s_mov_b32 m0, s20
	s_nop 0
	buffer_load_dwordx4 v153, s[8:11], s61 offen lds
	s_mov_b32 m0, s21
	s_nop 0
	buffer_load_dwordx4 v156, s[8:11], s61 offen lds
	s_mov_b32 m0, s1
	s_nop 0
	buffer_load_dwordx4 v151, s[48:51], s60 offen lds
	s_mov_b32 m0, s26
	s_nop 0
	buffer_load_dwordx4 v155, s[48:51], s60 offen lds
	s_waitcnt vmcnt(8)
	s_waitcnt lgkmcnt(0)
	s_barrier
	s_setprio 1
	s_waitcnt lgkmcnt(0)
	v_mfma_f32_16x16x32_f16 v[54:57], v[164:167], v[196:199], 0
	v_mfma_f32_16x16x32_f16 v[66:69], v[168:171], v[196:199], 0
	v_mfma_f32_16x16x32_f16 v[30:33], v[164:167], v[204:207], 0
	v_mfma_f32_16x16x32_f16 v[38:41], v[168:171], v[204:207], 0
	v_mfma_f32_16x16x32_f16 v[10:13], v[164:167], v[216:219], 0
	v_mfma_f32_16x16x32_f16 v[18:21], v[168:171], v[216:219], 0
	v_mfma_f32_16x16x32_f16 v[2:5], v[164:167], v[220:223], 0
	v_mfma_f32_16x16x32_f16 v[6:9], v[168:171], v[220:223], 0
	v_mfma_f32_16x16x32_f16 v[54:57], v[172:175], v[208:211], v[54:57]
	v_mfma_f32_16x16x32_f16 v[66:69], v[176:179], v[208:211], v[66:69]
	v_mfma_f32_16x16x32_f16 v[30:33], v[172:175], v[212:215], v[30:33]
	v_mfma_f32_16x16x32_f16 v[38:41], v[176:179], v[212:215], v[38:41]
	v_mfma_f32_16x16x32_f16 v[10:13], v[172:175], v[224:227], v[10:13]
	v_mfma_f32_16x16x32_f16 v[18:21], v[176:179], v[224:227], v[18:21]
	v_mfma_f32_16x16x32_f16 v[2:5], v[172:175], v[228:231], v[2:5]
	v_mfma_f32_16x16x32_f16 v[6:9], v[176:179], v[228:231], v[6:9]
	s_setprio 0
	s_setprio 1
	v_mfma_f32_16x16x32_f16 v[106:109], v[180:183], v[196:199], 0
	v_mfma_f32_16x16x32_f16 v[114:117], v[184:187], v[196:199], 0
	v_mfma_f32_16x16x32_f16 v[82:85], v[180:183], v[204:207], 0
	v_mfma_f32_16x16x32_f16 v[90:93], v[184:187], v[204:207], 0
	v_mfma_f32_16x16x32_f16 v[46:49], v[180:183], v[216:219], 0
	v_mfma_f32_16x16x32_f16 v[58:61], v[184:187], v[216:219], 0
	v_mfma_f32_16x16x32_f16 v[26:29], v[180:183], v[220:223], 0
	v_mfma_f32_16x16x32_f16 v[50:53], v[184:187], v[220:223], 0
	v_mfma_f32_16x16x32_f16 v[106:109], v[188:191], v[208:211], v[106:109]
	v_mfma_f32_16x16x32_f16 v[114:117], v[192:195], v[208:211], v[114:117]
	v_mfma_f32_16x16x32_f16 v[82:85], v[188:191], v[212:215], v[82:85]
	v_mfma_f32_16x16x32_f16 v[90:93], v[192:195], v[212:215], v[90:93]
	v_mfma_f32_16x16x32_f16 v[46:49], v[188:191], v[224:227], v[46:49]
	v_mfma_f32_16x16x32_f16 v[58:61], v[192:195], v[224:227], v[58:61]
	v_mfma_f32_16x16x32_f16 v[26:29], v[188:191], v[228:231], v[26:29]
	v_mfma_f32_16x16x32_f16 v[50:53], v[192:195], v[228:231], v[50:53]
	s_setprio 0
	s_barrier
	s_add_i32 s61, 0, 0x18000
	v_add_u32_e32 v0, s61, v157
	v_add_u32_e32 v147, s61, v158
	s_add_i32 s61, 0, 0x1c000
	ds_read_b128 v[164:167], v0
	ds_read_b128 v[168:171], v0 offset:2048
	ds_read_b128 v[172:175], v147
	ds_read_b128 v[176:179], v147 offset:2048
	v_add_u32_e32 v0, s61, v157
	v_add_u32_e32 v147, s61, v158
	ds_read_b128 v[180:183], v0
	ds_read_b128 v[184:187], v0 offset:2048
	ds_read_b128 v[188:191], v147
	ds_read_b128 v[192:195], v147 offset:2048
	s_add_i32 s60, s60, 0x80000
	s_mov_b32 m0, s27
	ds_read_b128 v[196:199], v161 offset:32768
	ds_read_b128 v[204:207], v161 offset:34816
	ds_read_b128 v[208:211], v162 offset:32768
	ds_read_b128 v[212:215], v162 offset:34816
	ds_read_b128 v[216:219], v161 offset:36864
	ds_read_b128 v[220:223], v161 offset:38912
	ds_read_b128 v[224:227], v162 offset:36864
	ds_read_b128 v[228:231], v162 offset:38912
	buffer_load_dwordx4 v151, s[48:51], s60 offen lds
	s_mov_b32 m0, s28
	s_nop 0
	buffer_load_dwordx4 v155, s[48:51], s60 offen lds
	s_waitcnt vmcnt(8)
	s_waitcnt lgkmcnt(0)
	s_barrier
	s_setprio 1
	s_waitcnt lgkmcnt(0)
	v_mfma_f32_16x16x32_f16 v[94:97], v[164:167], v[196:199], v[94:97]
	v_mfma_f32_16x16x32_f16 v[98:101], v[168:171], v[196:199], v[98:101]
	v_mfma_f32_16x16x32_f16 v[62:65], v[164:167], v[204:207], v[62:65]
	v_mfma_f32_16x16x32_f16 v[74:77], v[168:171], v[204:207], v[74:77]
	v_mfma_f32_16x16x32_f16 v[34:37], v[164:167], v[216:219], v[34:37]
	v_mfma_f32_16x16x32_f16 v[42:45], v[168:171], v[216:219], v[42:45]
	v_mfma_f32_16x16x32_f16 v[14:17], v[164:167], v[220:223], v[14:17]
	v_mfma_f32_16x16x32_f16 v[22:25], v[168:171], v[220:223], v[22:25]
	v_mfma_f32_16x16x32_f16 v[94:97], v[172:175], v[208:211], v[94:97]
	v_mfma_f32_16x16x32_f16 v[98:101], v[176:179], v[208:211], v[98:101]
	v_mfma_f32_16x16x32_f16 v[62:65], v[172:175], v[212:215], v[62:65]
	v_mfma_f32_16x16x32_f16 v[74:77], v[176:179], v[212:215], v[74:77]
	v_mfma_f32_16x16x32_f16 v[34:37], v[172:175], v[224:227], v[34:37]
	v_mfma_f32_16x16x32_f16 v[42:45], v[176:179], v[224:227], v[42:45]
	v_mfma_f32_16x16x32_f16 v[14:17], v[172:175], v[228:231], v[14:17]
	v_mfma_f32_16x16x32_f16 v[22:25], v[176:179], v[228:231], v[22:25]
	s_setprio 0
	s_setprio 1
	v_mfma_f32_16x16x32_f16 v[122:125], v[180:183], v[196:199], v[122:125]
	v_mfma_f32_16x16x32_f16 v[126:129], v[184:187], v[196:199], v[126:129]
	v_mfma_f32_16x16x32_f16 v[110:113], v[180:183], v[204:207], v[110:113]
	v_mfma_f32_16x16x32_f16 v[118:121], v[184:187], v[204:207], v[118:121]
	v_mfma_f32_16x16x32_f16 v[86:89], v[180:183], v[216:219], v[86:89]
	v_mfma_f32_16x16x32_f16 v[102:105], v[184:187], v[216:219], v[102:105]
	v_mfma_f32_16x16x32_f16 v[70:73], v[180:183], v[220:223], v[70:73]
	v_mfma_f32_16x16x32_f16 v[78:81], v[184:187], v[220:223], v[78:81]
	v_mfma_f32_16x16x32_f16 v[122:125], v[188:191], v[208:211], v[122:125]
	v_mfma_f32_16x16x32_f16 v[126:129], v[192:195], v[208:211], v[126:129]
	v_mfma_f32_16x16x32_f16 v[110:113], v[188:191], v[212:215], v[110:113]
	v_mfma_f32_16x16x32_f16 v[118:121], v[192:195], v[212:215], v[118:121]
	v_mfma_f32_16x16x32_f16 v[86:89], v[188:191], v[224:227], v[86:89]
	v_mfma_f32_16x16x32_f16 v[102:105], v[192:195], v[224:227], v[102:105]
	v_mfma_f32_16x16x32_f16 v[70:73], v[188:191], v[228:231], v[70:73]
	v_mfma_f32_16x16x32_f16 v[78:81], v[192:195], v[228:231], v[78:81]
	s_setprio 0
	s_barrier
	s_mov_b32 m0, s29
	ds_read_b128 v[196:199], v161 offset:49152
	ds_read_b128 v[204:207], v161 offset:51200
	ds_read_b128 v[208:211], v162 offset:49152
	ds_read_b128 v[212:215], v162 offset:51200
	ds_read_b128 v[216:219], v161 offset:53248
	ds_read_b128 v[220:223], v161 offset:55296
	ds_read_b128 v[224:227], v162 offset:53248
	ds_read_b128 v[228:231], v162 offset:55296
	buffer_load_dwordx4 v153, s[8:11], s58 offen lds
	s_mov_b32 m0, s30
	s_add_i32 s55, s55, 0x80080
	buffer_load_dwordx4 v156, s[8:11], s58 offen lds
	s_mov_b32 m0, s35
	s_nop 0
	buffer_load_dwordx4 v153, s[8:11], s55 offen lds
	s_mov_b32 m0, s36
	s_nop 0
	buffer_load_dwordx4 v156, s[8:11], s55 offen lds
	s_mov_b32 m0, s31
	s_nop 0
	buffer_load_dwordx4 v151, s[48:51], s56 offen lds
	s_mov_b32 m0, s34
	s_nop 0
	buffer_load_dwordx4 v155, s[48:51], s56 offen lds
	s_waitcnt vmcnt(8)
	s_waitcnt lgkmcnt(0)
	s_barrier
	s_setprio 1
	s_waitcnt lgkmcnt(0)
	v_mfma_f32_16x16x32_f16 v[54:57], v[164:167], v[196:199], v[54:57]
	v_mfma_f32_16x16x32_f16 v[66:69], v[168:171], v[196:199], v[66:69]
	v_mfma_f32_16x16x32_f16 v[30:33], v[164:167], v[204:207], v[30:33]
	v_mfma_f32_16x16x32_f16 v[38:41], v[168:171], v[204:207], v[38:41]
	v_mfma_f32_16x16x32_f16 v[10:13], v[164:167], v[216:219], v[10:13]
	v_mfma_f32_16x16x32_f16 v[18:21], v[168:171], v[216:219], v[18:21]
	v_mfma_f32_16x16x32_f16 v[2:5], v[164:167], v[220:223], v[2:5]
	v_mfma_f32_16x16x32_f16 v[6:9], v[168:171], v[220:223], v[6:9]
	v_mfma_f32_16x16x32_f16 v[54:57], v[172:175], v[208:211], v[54:57]
	v_mfma_f32_16x16x32_f16 v[66:69], v[176:179], v[208:211], v[66:69]
	v_mfma_f32_16x16x32_f16 v[30:33], v[172:175], v[212:215], v[30:33]
	v_mfma_f32_16x16x32_f16 v[38:41], v[176:179], v[212:215], v[38:41]
	v_mfma_f32_16x16x32_f16 v[10:13], v[172:175], v[224:227], v[10:13]
	v_mfma_f32_16x16x32_f16 v[18:21], v[176:179], v[224:227], v[18:21]
	v_mfma_f32_16x16x32_f16 v[2:5], v[172:175], v[228:231], v[2:5]
	v_mfma_f32_16x16x32_f16 v[6:9], v[176:179], v[228:231], v[6:9]
	s_setprio 0
	s_setprio 1
	v_mfma_f32_16x16x32_f16 v[106:109], v[180:183], v[196:199], v[106:109]
	v_mfma_f32_16x16x32_f16 v[114:117], v[184:187], v[196:199], v[114:117]
	v_mfma_f32_16x16x32_f16 v[82:85], v[180:183], v[204:207], v[82:85]
	v_mfma_f32_16x16x32_f16 v[90:93], v[184:187], v[204:207], v[90:93]
	v_mfma_f32_16x16x32_f16 v[46:49], v[180:183], v[216:219], v[46:49]
	v_mfma_f32_16x16x32_f16 v[58:61], v[184:187], v[216:219], v[58:61]
	v_mfma_f32_16x16x32_f16 v[26:29], v[180:183], v[220:223], v[26:29]
	v_mfma_f32_16x16x32_f16 v[50:53], v[184:187], v[220:223], v[50:53]
	v_mfma_f32_16x16x32_f16 v[106:109], v[188:191], v[208:211], v[106:109]
	v_mfma_f32_16x16x32_f16 v[114:117], v[192:195], v[208:211], v[114:117]
	v_mfma_f32_16x16x32_f16 v[82:85], v[188:191], v[212:215], v[82:85]
	v_mfma_f32_16x16x32_f16 v[90:93], v[192:195], v[212:215], v[90:93]
	v_mfma_f32_16x16x32_f16 v[46:49], v[188:191], v[224:227], v[46:49]
	v_mfma_f32_16x16x32_f16 v[58:61], v[192:195], v[224:227], v[58:61]
	v_mfma_f32_16x16x32_f16 v[26:29], v[188:191], v[228:231], v[26:29]
	v_mfma_f32_16x16x32_f16 v[50:53], v[192:195], v[228:231], v[50:53]
	s_setprio 0
	s_barrier
	s_branch .Lc0b_tail
.LBB0_162:
	s_cmp_eq_u32 s54, -2
	s_cbranch_scc1 .Lc0b_first
	s_add_i32 s55, s52, 0xfff80080
	s_and_b64 s[10:11], s[10:11], exec
	s_cselect_b32 s60, s46, s55
	s_cselect_b32 s55, s47, s53
	s_add_i32 s10, 0, 0x10000
	v_add_u32_e32 v0, s10, v157
	v_add_u32_e32 v147, s10, v158
	s_add_i32 s10, 0, 0x14000
	ds_read_b128 v[164:167], v0
	ds_read_b128 v[168:171], v0 offset:2048
	ds_read_b128 v[172:175], v147
	ds_read_b128 v[176:179], v147 offset:2048
	v_add_u32_e32 v0, s10, v157
	v_add_u32_e32 v147, s10, v158
	ds_read_b128 v[180:183], v0
	ds_read_b128 v[184:187], v0 offset:2048
	ds_read_b128 v[188:191], v147
	ds_read_b128 v[192:195], v147 offset:2048
	s_or_b32 s56, s60, 0x80
	s_or_b32 s58, s55, 0x80
	s_mov_b32 m0, s37
	ds_read_b128 v[196:199], v161
	ds_read_b128 v[204:207], v161 offset:2048
	ds_read_b128 v[208:211], v162
	ds_read_b128 v[212:215], v162 offset:2048
	ds_read_b128 v[216:219], v161 offset:4096
	ds_read_b128 v[220:223], v161 offset:6144
	ds_read_b128 v[224:227], v162 offset:4096
	ds_read_b128 v[228:231], v162 offset:6144
	buffer_load_dwordx4 v151, s[48:51], s52 offen lds
	s_mov_b32 m0, s38
	s_nop 0
	buffer_load_dwordx4 v155, s[48:51], s52 offen lds
	s_waitcnt vmcnt(8)
	s_waitcnt lgkmcnt(0)
	s_barrier
	s_setprio 1
	s_waitcnt lgkmcnt(0)
	v_mfma_f32_16x16x32_f16 v[94:97], v[164:167], v[196:199], v[94:97]
	v_mfma_f32_16x16x32_f16 v[98:101], v[168:171], v[196:199], v[98:101]
	v_mfma_f32_16x16x32_f16 v[62:65], v[164:167], v[204:207], v[62:65]
	v_mfma_f32_16x16x32_f16 v[74:77], v[168:171], v[204:207], v[74:77]
	v_mfma_f32_16x16x32_f16 v[34:37], v[164:167], v[216:219], v[34:37]
	v_mfma_f32_16x16x32_f16 v[42:45], v[168:171], v[216:219], v[42:45]
	v_mfma_f32_16x16x32_f16 v[14:17], v[164:167], v[220:223], v[14:17]
	v_mfma_f32_16x16x32_f16 v[22:25], v[168:171], v[220:223], v[22:25]
	v_mfma_f32_16x16x32_f16 v[94:97], v[172:175], v[208:211], v[94:97]
	v_mfma_f32_16x16x32_f16 v[98:101], v[176:179], v[208:211], v[98:101]
	v_mfma_f32_16x16x32_f16 v[62:65], v[172:175], v[212:215], v[62:65]
	v_mfma_f32_16x16x32_f16 v[74:77], v[176:179], v[212:215], v[74:77]
	v_mfma_f32_16x16x32_f16 v[34:37], v[172:175], v[224:227], v[34:37]
	v_mfma_f32_16x16x32_f16 v[42:45], v[176:179], v[224:227], v[42:45]
	v_mfma_f32_16x16x32_f16 v[14:17], v[172:175], v[228:231], v[14:17]
	v_mfma_f32_16x16x32_f16 v[22:25], v[176:179], v[228:231], v[22:25]
	s_setprio 0
	s_setprio 1
	v_mfma_f32_16x16x32_f16 v[122:125], v[180:183], v[196:199], v[122:125]
	v_mfma_f32_16x16x32_f16 v[126:129], v[184:187], v[196:199], v[126:129]
	v_mfma_f32_16x16x32_f16 v[110:113], v[180:183], v[204:207], v[110:113]
	v_mfma_f32_16x16x32_f16 v[118:121], v[184:187], v[204:207], v[118:121]
	v_mfma_f32_16x16x32_f16 v[86:89], v[180:183], v[216:219], v[86:89]
	v_mfma_f32_16x16x32_f16 v[102:105], v[184:187], v[216:219], v[102:105]
	v_mfma_f32_16x16x32_f16 v[70:73], v[180:183], v[220:223], v[70:73]
	v_mfma_f32_16x16x32_f16 v[78:81], v[184:187], v[220:223], v[78:81]
	v_mfma_f32_16x16x32_f16 v[122:125], v[188:191], v[208:211], v[122:125]
	v_mfma_f32_16x16x32_f16 v[126:129], v[192:195], v[208:211], v[126:129]
	v_mfma_f32_16x16x32_f16 v[110:113], v[188:191], v[212:215], v[110:113]
	v_mfma_f32_16x16x32_f16 v[118:121], v[192:195], v[212:215], v[118:121]
	v_mfma_f32_16x16x32_f16 v[86:89], v[188:191], v[224:227], v[86:89]
	v_mfma_f32_16x16x32_f16 v[102:105], v[192:195], v[224:227], v[102:105]
	v_mfma_f32_16x16x32_f16 v[70:73], v[188:191], v[228:231], v[70:73]
	v_mfma_f32_16x16x32_f16 v[78:81], v[192:195], v[228:231], v[78:81]
	s_setprio 0
	s_barrier
	s_mov_b32 m0, s2
	s_mov_b32 s10, s50
	s_mov_b32 s11, s51
	ds_read_b128 v[196:199], v161 offset:16384
	ds_read_b128 v[204:207], v161 offset:18432
	ds_read_b128 v[208:211], v162 offset:16384
	ds_read_b128 v[212:215], v162 offset:18432
	ds_read_b128 v[216:219], v161 offset:20480
	ds_read_b128 v[220:223], v161 offset:22528
	ds_read_b128 v[224:227], v162 offset:20480
	ds_read_b128 v[228:231], v162 offset:22528
	buffer_load_dwordx4 v153, s[8:11], s55 offen lds
	s_mov_b32 m0, s3
	s_add_i32 s61, s55, 0x80000
	buffer_load_dwordx4 v156, s[8:11], s55 offen lds
	s_mov_b32 m0, s20
	s_nop 0
	buffer_load_dwordx4 v153, s[8:11], s61 offen lds
	s_mov_b32 m0, s21
	s_nop 0
	buffer_load_dwordx4 v156, s[8:11], s61 offen lds
	s_mov_b32 m0, s1
	s_nop 0
	buffer_load_dwordx4 v151, s[48:51], s60 offen lds
	s_mov_b32 m0, s26
	s_nop 0
	buffer_load_dwordx4 v155, s[48:51], s60 offen lds
	s_waitcnt vmcnt(8)
	s_waitcnt lgkmcnt(0)
	s_barrier
	s_setprio 1
	s_waitcnt lgkmcnt(0)
	v_mfma_f32_16x16x32_f16 v[54:57], v[164:167], v[196:199], v[54:57]
	v_mfma_f32_16x16x32_f16 v[66:69], v[168:171], v[196:199], v[66:69]
	v_mfma_f32_16x16x32_f16 v[30:33], v[164:167], v[204:207], v[30:33]
	v_mfma_f32_16x16x32_f16 v[38:41], v[168:171], v[204:207], v[38:41]
	v_mfma_f32_16x16x32_f16 v[10:13], v[164:167], v[216:219], v[10:13]
	v_mfma_f32_16x16x32_f16 v[18:21], v[168:171], v[216:219], v[18:21]
	v_mfma_f32_16x16x32_f16 v[2:5], v[164:167], v[220:223], v[2:5]
	v_mfma_f32_16x16x32_f16 v[6:9], v[168:171], v[220:223], v[6:9]
	v_mfma_f32_16x16x32_f16 v[54:57], v[172:175], v[208:211], v[54:57]
	v_mfma_f32_16x16x32_f16 v[66:69], v[176:179], v[208:211], v[66:69]
	v_mfma_f32_16x16x32_f16 v[30:33], v[172:175], v[212:215], v[30:33]
	v_mfma_f32_16x16x32_f16 v[38:41], v[176:179], v[212:215], v[38:41]
	v_mfma_f32_16x16x32_f16 v[10:13], v[172:175], v[224:227], v[10:13]
	v_mfma_f32_16x16x32_f16 v[18:21], v[176:179], v[224:227], v[18:21]
	v_mfma_f32_16x16x32_f16 v[2:5], v[172:175], v[228:231], v[2:5]
	v_mfma_f32_16x16x32_f16 v[6:9], v[176:179], v[228:231], v[6:9]
	s_setprio 0
	s_setprio 1
	v_mfma_f32_16x16x32_f16 v[106:109], v[180:183], v[196:199], v[106:109]
	v_mfma_f32_16x16x32_f16 v[114:117], v[184:187], v[196:199], v[114:117]
	v_mfma_f32_16x16x32_f16 v[82:85], v[180:183], v[204:207], v[82:85]
	v_mfma_f32_16x16x32_f16 v[90:93], v[184:187], v[204:207], v[90:93]
	v_mfma_f32_16x16x32_f16 v[46:49], v[180:183], v[216:219], v[46:49]
	v_mfma_f32_16x16x32_f16 v[58:61], v[184:187], v[216:219], v[58:61]
	v_mfma_f32_16x16x32_f16 v[26:29], v[180:183], v[220:223], v[26:29]
	v_mfma_f32_16x16x32_f16 v[50:53], v[184:187], v[220:223], v[50:53]
	v_mfma_f32_16x16x32_f16 v[106:109], v[188:191], v[208:211], v[106:109]
	v_mfma_f32_16x16x32_f16 v[114:117], v[192:195], v[208:211], v[114:117]
	v_mfma_f32_16x16x32_f16 v[82:85], v[188:191], v[212:215], v[82:85]
	v_mfma_f32_16x16x32_f16 v[90:93], v[192:195], v[212:215], v[90:93]
	v_mfma_f32_16x16x32_f16 v[46:49], v[188:191], v[224:227], v[46:49]
	v_mfma_f32_16x16x32_f16 v[58:61], v[192:195], v[224:227], v[58:61]
	v_mfma_f32_16x16x32_f16 v[26:29], v[188:191], v[228:231], v[26:29]
	v_mfma_f32_16x16x32_f16 v[50:53], v[192:195], v[228:231], v[50:53]
	s_setprio 0
	s_barrier
	s_add_i32 s61, 0, 0x18000
	v_add_u32_e32 v0, s61, v157
	v_add_u32_e32 v147, s61, v158
	s_add_i32 s61, 0, 0x1c000
	ds_read_b128 v[164:167], v0
	ds_read_b128 v[168:171], v0 offset:2048
	ds_read_b128 v[172:175], v147
	ds_read_b128 v[176:179], v147 offset:2048
	v_add_u32_e32 v0, s61, v157
	v_add_u32_e32 v147, s61, v158
	ds_read_b128 v[180:183], v0
	ds_read_b128 v[184:187], v0 offset:2048
	ds_read_b128 v[188:191], v147
	ds_read_b128 v[192:195], v147 offset:2048
	s_add_i32 s60, s60, 0x80000
	s_mov_b32 m0, s27
	ds_read_b128 v[196:199], v161 offset:32768
	ds_read_b128 v[204:207], v161 offset:34816
	ds_read_b128 v[208:211], v162 offset:32768
	ds_read_b128 v[212:215], v162 offset:34816
	ds_read_b128 v[216:219], v161 offset:36864
	ds_read_b128 v[220:223], v161 offset:38912
	ds_read_b128 v[224:227], v162 offset:36864
	ds_read_b128 v[228:231], v162 offset:38912
	buffer_load_dwordx4 v151, s[48:51], s60 offen lds
	s_mov_b32 m0, s28
	s_nop 0
	buffer_load_dwordx4 v155, s[48:51], s60 offen lds
	s_waitcnt vmcnt(8)
	s_waitcnt lgkmcnt(0)
	s_barrier
	s_setprio 1
	s_waitcnt lgkmcnt(0)
	v_mfma_f32_16x16x32_f16 v[94:97], v[164:167], v[196:199], v[94:97]
	v_mfma_f32_16x16x32_f16 v[98:101], v[168:171], v[196:199], v[98:101]
	v_mfma_f32_16x16x32_f16 v[62:65], v[164:167], v[204:207], v[62:65]
	v_mfma_f32_16x16x32_f16 v[74:77], v[168:171], v[204:207], v[74:77]
	v_mfma_f32_16x16x32_f16 v[34:37], v[164:167], v[216:219], v[34:37]
	v_mfma_f32_16x16x32_f16 v[42:45], v[168:171], v[216:219], v[42:45]
	v_mfma_f32_16x16x32_f16 v[14:17], v[164:167], v[220:223], v[14:17]
	v_mfma_f32_16x16x32_f16 v[22:25], v[168:171], v[220:223], v[22:25]
	v_mfma_f32_16x16x32_f16 v[94:97], v[172:175], v[208:211], v[94:97]
	v_mfma_f32_16x16x32_f16 v[98:101], v[176:179], v[208:211], v[98:101]
	v_mfma_f32_16x16x32_f16 v[62:65], v[172:175], v[212:215], v[62:65]
	v_mfma_f32_16x16x32_f16 v[74:77], v[176:179], v[212:215], v[74:77]
	v_mfma_f32_16x16x32_f16 v[34:37], v[172:175], v[224:227], v[34:37]
	v_mfma_f32_16x16x32_f16 v[42:45], v[176:179], v[224:227], v[42:45]
	v_mfma_f32_16x16x32_f16 v[14:17], v[172:175], v[228:231], v[14:17]
	v_mfma_f32_16x16x32_f16 v[22:25], v[176:179], v[228:231], v[22:25]
	s_setprio 0
	s_setprio 1
	v_mfma_f32_16x16x32_f16 v[122:125], v[180:183], v[196:199], v[122:125]
	v_mfma_f32_16x16x32_f16 v[126:129], v[184:187], v[196:199], v[126:129]
	v_mfma_f32_16x16x32_f16 v[110:113], v[180:183], v[204:207], v[110:113]
	v_mfma_f32_16x16x32_f16 v[118:121], v[184:187], v[204:207], v[118:121]
	v_mfma_f32_16x16x32_f16 v[86:89], v[180:183], v[216:219], v[86:89]
	v_mfma_f32_16x16x32_f16 v[102:105], v[184:187], v[216:219], v[102:105]
	v_mfma_f32_16x16x32_f16 v[70:73], v[180:183], v[220:223], v[70:73]
	v_mfma_f32_16x16x32_f16 v[78:81], v[184:187], v[220:223], v[78:81]
	v_mfma_f32_16x16x32_f16 v[122:125], v[188:191], v[208:211], v[122:125]
	v_mfma_f32_16x16x32_f16 v[126:129], v[192:195], v[208:211], v[126:129]
	v_mfma_f32_16x16x32_f16 v[110:113], v[188:191], v[212:215], v[110:113]
	v_mfma_f32_16x16x32_f16 v[118:121], v[192:195], v[212:215], v[118:121]
	v_mfma_f32_16x16x32_f16 v[86:89], v[188:191], v[224:227], v[86:89]
	v_mfma_f32_16x16x32_f16 v[102:105], v[192:195], v[224:227], v[102:105]
	v_mfma_f32_16x16x32_f16 v[70:73], v[188:191], v[228:231], v[70:73]
	v_mfma_f32_16x16x32_f16 v[78:81], v[192:195], v[228:231], v[78:81]
	s_setprio 0
	s_barrier
	s_mov_b32 m0, s29
	ds_read_b128 v[196:199], v161 offset:49152
	ds_read_b128 v[204:207], v161 offset:51200
	ds_read_b128 v[208:211], v162 offset:49152
	ds_read_b128 v[212:215], v162 offset:51200
	ds_read_b128 v[216:219], v161 offset:53248
	ds_read_b128 v[220:223], v161 offset:55296
	ds_read_b128 v[224:227], v162 offset:53248
	ds_read_b128 v[228:231], v162 offset:55296
	buffer_load_dwordx4 v153, s[8:11], s58 offen lds
	s_mov_b32 m0, s30
	s_add_i32 s55, s55, 0x80080
	buffer_load_dwordx4 v156, s[8:11], s58 offen lds
	s_mov_b32 m0, s35
	s_nop 0
	buffer_load_dwordx4 v153, s[8:11], s55 offen lds
	s_mov_b32 m0, s36
	s_nop 0
	buffer_load_dwordx4 v156, s[8:11], s55 offen lds
	s_mov_b32 m0, s31
	s_nop 0
	buffer_load_dwordx4 v151, s[48:51], s56 offen lds
	s_mov_b32 m0, s34
	s_nop 0
	buffer_load_dwordx4 v155, s[48:51], s56 offen lds
	s_waitcnt vmcnt(8)
	s_waitcnt lgkmcnt(0)
	s_barrier
	s_setprio 1
	s_waitcnt lgkmcnt(0)
	v_mfma_f32_16x16x32_f16 v[54:57], v[164:167], v[196:199], v[54:57]
	v_mfma_f32_16x16x32_f16 v[66:69], v[168:171], v[196:199], v[66:69]
	v_mfma_f32_16x16x32_f16 v[30:33], v[164:167], v[204:207], v[30:33]
	v_mfma_f32_16x16x32_f16 v[38:41], v[168:171], v[204:207], v[38:41]
	v_mfma_f32_16x16x32_f16 v[10:13], v[164:167], v[216:219], v[10:13]
	v_mfma_f32_16x16x32_f16 v[18:21], v[168:171], v[216:219], v[18:21]
	v_mfma_f32_16x16x32_f16 v[2:5], v[164:167], v[220:223], v[2:5]
	v_mfma_f32_16x16x32_f16 v[6:9], v[168:171], v[220:223], v[6:9]
	v_mfma_f32_16x16x32_f16 v[54:57], v[172:175], v[208:211], v[54:57]
	v_mfma_f32_16x16x32_f16 v[66:69], v[176:179], v[208:211], v[66:69]
	v_mfma_f32_16x16x32_f16 v[30:33], v[172:175], v[212:215], v[30:33]
	v_mfma_f32_16x16x32_f16 v[38:41], v[176:179], v[212:215], v[38:41]
	v_mfma_f32_16x16x32_f16 v[10:13], v[172:175], v[224:227], v[10:13]
	v_mfma_f32_16x16x32_f16 v[18:21], v[176:179], v[224:227], v[18:21]
	v_mfma_f32_16x16x32_f16 v[2:5], v[172:175], v[228:231], v[2:5]
	v_mfma_f32_16x16x32_f16 v[6:9], v[176:179], v[228:231], v[6:9]
	s_setprio 0
	s_setprio 1
	v_mfma_f32_16x16x32_f16 v[106:109], v[180:183], v[196:199], v[106:109]
	v_mfma_f32_16x16x32_f16 v[114:117], v[184:187], v[196:199], v[114:117]
	v_mfma_f32_16x16x32_f16 v[82:85], v[180:183], v[204:207], v[82:85]
	v_mfma_f32_16x16x32_f16 v[90:93], v[184:187], v[204:207], v[90:93]
	v_mfma_f32_16x16x32_f16 v[46:49], v[180:183], v[216:219], v[46:49]
	v_mfma_f32_16x16x32_f16 v[58:61], v[184:187], v[216:219], v[58:61]
	v_mfma_f32_16x16x32_f16 v[26:29], v[180:183], v[220:223], v[26:29]
	v_mfma_f32_16x16x32_f16 v[50:53], v[184:187], v[220:223], v[50:53]
	v_mfma_f32_16x16x32_f16 v[106:109], v[188:191], v[208:211], v[106:109]
	v_mfma_f32_16x16x32_f16 v[114:117], v[192:195], v[208:211], v[114:117]
	v_mfma_f32_16x16x32_f16 v[82:85], v[188:191], v[212:215], v[82:85]
	v_mfma_f32_16x16x32_f16 v[90:93], v[192:195], v[212:215], v[90:93]
	v_mfma_f32_16x16x32_f16 v[46:49], v[188:191], v[224:227], v[46:49]
	v_mfma_f32_16x16x32_f16 v[58:61], v[192:195], v[224:227], v[58:61]
	v_mfma_f32_16x16x32_f16 v[26:29], v[188:191], v[228:231], v[26:29]
	v_mfma_f32_16x16x32_f16 v[50:53], v[192:195], v[228:231], v[50:53]
	s_setprio 0
	s_barrier
.Lc0b_tail:
	s_add_i32 s54, s54, 2
	s_addk_i32 s52, 0x100
	s_addk_i32 s53, 0x100
	s_cmp_gt_u32 s54, 29
	s_cbranch_scc1 .LBB0_165

.LBB0_167:
	s_waitcnt vmcnt(16)
	v_lshl_or_b32 v148, s45, 8, v160
	v_alignbit_b32 v0, v131, v130, 24
	v_and_b32_e32 v147, 0xffffff, v130
	v_cvt_f32_u32_e32 v0, v0
	v_cvt_f32_u32_e32 v147, v147
	v_alignbit_b32 v149, v133, v132, 24
	v_and_b32_e32 v150, 0xffffff, v132
	v_cvt_f32_u32_e32 v149, v149
	v_cvt_f32_u32_e32 v150, v150
	v_fmac_f32_e32 v0, 0x33800000, v147
	v_fmamk_f32 v0, v0, 0x3a000000, v200
	v_rsq_f32_e32 v164, v0
	v_fmac_f32_e32 v149, 0x33800000, v150
	v_fmamk_f32 v0, v149, 0x3a000000, v200
	v_rsq_f32_e32 v166, v0
	v_alignbit_b32 v0, v135, v134, 24
	v_and_b32_e32 v147, 0xffffff, v134
	v_cvt_f32_u32_e32 v0, v0
	v_cvt_f32_u32_e32 v147, v147
	v_alignbit_b32 v149, v137, v136, 24
	v_and_b32_e32 v150, 0xffffff, v136
	v_cvt_f32_u32_e32 v149, v149
	v_cvt_f32_u32_e32 v150, v150
	v_fmac_f32_e32 v0, 0x33800000, v147
	v_fmamk_f32 v0, v0, 0x3a000000, v200
	v_rsq_f32_e32 v168, v0
	v_fmac_f32_e32 v149, 0x33800000, v150
	v_fmamk_f32 v0, v149, 0x3a000000, v200
	v_rsq_f32_e32 v170, v0
	v_alignbit_b32 v0, v139, v138, 24
	v_and_b32_e32 v147, 0xffffff, v138
	v_cvt_f32_u32_e32 v0, v0
	v_cvt_f32_u32_e32 v147, v147
	v_alignbit_b32 v149, v141, v140, 24
	v_and_b32_e32 v150, 0xffffff, v140
	v_cvt_f32_u32_e32 v149, v149
	v_cvt_f32_u32_e32 v150, v150
	v_fmac_f32_e32 v0, 0x33800000, v147
	v_fmamk_f32 v0, v0, 0x3a000000, v200
	v_rsq_f32_e32 v154, v0
	v_fmac_f32_e32 v149, 0x33800000, v150
	v_fmamk_f32 v0, v149, 0x3a000000, v200
	v_rsq_f32_e32 v152, v0
	v_alignbit_b32 v0, v143, v142, 24
	v_and_b32_e32 v147, 0xffffff, v142
	v_cvt_f32_u32_e32 v0, v0
	v_cvt_f32_u32_e32 v147, v147
	v_alignbit_b32 v149, v145, v144, 24
	v_and_b32_e32 v150, 0xffffff, v144
	v_cvt_f32_u32_e32 v149, v149
	v_cvt_f32_u32_e32 v163, v150
	v_fmac_f32_e32 v0, 0x33800000, v147
	v_fmamk_f32 v0, v0, 0x3a000000, v200
	v_rsq_f32_e32 v150, v0
	v_fmac_f32_e32 v149, 0x33800000, v163
	v_fmamk_f32 v0, v149, 0x3a000000, v200
	v_ashrrev_i32_e32 v149, 31, v148
	v_mad_i64_i32 v[172:173], s[10:11], v146, s22, 0
	v_lshl_add_u64 v[172:173], v[172:173], 1, s[16:17]
	v_lshlrev_b64 v[148:149], 1, v[148:149]
	v_pk_mul_f32 v[94:95], v[94:95], v[164:165] op_sel_hi:[1,0]
	v_lshl_add_u64 v[172:173], v[172:173], 0, v[148:149]
	v_pk_mul_f32 v[96:97], v[96:97], v[164:165] op_sel_hi:[1,0]
	v_cvt_pk_bf16_f32 v94, v94, v95
	v_pk_mul_f32 v[100:101], v[100:101], v[164:165] op_sel_hi:[1,0]
	v_cvt_pk_bf16_f32 v95, v96, v97
	v_pk_mul_f32 v[98:99], v[98:99], v[164:165] op_sel_hi:[1,0]
	v_pk_mul_f32 v[62:63], v[62:63], v[166:167] op_sel_hi:[1,0]
	v_cvt_pk_bf16_f32 v96, v98, v99
	v_cvt_pk_bf16_f32 v97, v100, v101
	global_store_dwordx4 v[172:173], v[94:97], off
	v_pk_mul_f32 v[98:99], v[128:129], v[164:165] op_sel_hi:[1,0]
	v_pk_mul_f32 v[100:101], v[126:127], v[164:165] op_sel_hi:[1,0]
	v_pk_mul_f32 v[94:95], v[122:123], v[164:165] op_sel_hi:[1,0]
	v_pk_mul_f32 v[96:97], v[124:125], v[164:165] op_sel_hi:[1,0]
	v_cvt_pk_bf16_f32 v94, v94, v95
	v_pk_mul_f32 v[64:65], v[64:65], v[166:167] op_sel_hi:[1,0]
	v_cvt_pk_bf16_f32 v95, v96, v97
	v_cvt_pk_bf16_f32 v96, v100, v101
	v_cvt_pk_bf16_f32 v97, v98, v99
	global_store_dwordx4 v[172:173], v[94:97], off offset:256
	v_cvt_pk_bf16_f32 v62, v62, v63
	v_cvt_pk_bf16_f32 v63, v64, v65
	v_pk_mul_f32 v[76:77], v[76:77], v[166:167] op_sel_hi:[1,0]
	v_pk_mul_f32 v[74:75], v[74:75], v[166:167] op_sel_hi:[1,0]
	v_or_b32_e32 v94, 16, v146
	v_mad_i64_i32 v[94:95], s[10:11], v94, s22, 0
	v_lshl_add_u64 v[94:95], v[94:95], 1, s[16:17]
	v_lshl_add_u64 v[94:95], v[94:95], 0, v[148:149]
	v_cvt_pk_bf16_f32 v64, v74, v75
	v_cvt_pk_bf16_f32 v65, v76, v77
	global_store_dwordx4 v[94:95], v[62:65], off
	v_pk_mul_f32 v[74:75], v[120:121], v[166:167] op_sel_hi:[1,0]
	v_pk_mul_f32 v[76:77], v[118:119], v[166:167] op_sel_hi:[1,0]
	v_pk_mul_f32 v[62:63], v[110:111], v[166:167] op_sel_hi:[1,0]
	v_pk_mul_f32 v[64:65], v[112:113], v[166:167] op_sel_hi:[1,0]
	v_cvt_pk_bf16_f32 v62, v62, v63
	v_pk_mul_f32 v[34:35], v[34:35], v[168:169] op_sel_hi:[1,0]
	v_cvt_pk_bf16_f32 v63, v64, v65
	v_cvt_pk_bf16_f32 v64, v76, v77
	v_cvt_pk_bf16_f32 v65, v74, v75
	global_store_dwordx4 v[94:95], v[62:65], off offset:256
	v_pk_mul_f32 v[36:37], v[36:37], v[168:169] op_sel_hi:[1,0]
	v_cvt_pk_bf16_f32 v34, v34, v35
	v_pk_mul_f32 v[44:45], v[44:45], v[168:169] op_sel_hi:[1,0]
	v_or_b32_e32 v62, 32, v146
	v_mad_i64_i32 v[62:63], s[10:11], v62, s22, 0
	v_lshl_add_u64 v[62:63], v[62:63], 1, s[16:17]
	v_lshl_add_u64 v[62:63], v[62:63], 0, v[148:149]
	v_cvt_pk_bf16_f32 v35, v36, v37
	v_pk_mul_f32 v[42:43], v[42:43], v[168:169] op_sel_hi:[1,0]
	v_pk_mul_f32 v[14:15], v[14:15], v[170:171] op_sel_hi:[1,0]
	v_cvt_pk_bf16_f32 v36, v42, v43
	v_cvt_pk_bf16_f32 v37, v44, v45
	global_store_dwordx4 v[62:63], v[34:37], off
	v_pk_mul_f32 v[42:43], v[104:105], v[168:169] op_sel_hi:[1,0]
	v_pk_mul_f32 v[44:45], v[102:103], v[168:169] op_sel_hi:[1,0]
	v_pk_mul_f32 v[34:35], v[86:87], v[168:169] op_sel_hi:[1,0]
	v_pk_mul_f32 v[36:37], v[88:89], v[168:169] op_sel_hi:[1,0]
	v_cvt_pk_bf16_f32 v34, v34, v35
	v_pk_mul_f32 v[16:17], v[16:17], v[170:171] op_sel_hi:[1,0]
	v_cvt_pk_bf16_f32 v35, v36, v37
	v_cvt_pk_bf16_f32 v36, v44, v45
	v_cvt_pk_bf16_f32 v37, v42, v43
	global_store_dwordx4 v[62:63], v[34:37], off offset:256
	v_cvt_pk_bf16_f32 v14, v14, v15
	v_cvt_pk_bf16_f32 v15, v16, v17
	v_pk_mul_f32 v[24:25], v[24:25], v[170:171] op_sel_hi:[1,0]
	v_pk_mul_f32 v[22:23], v[22:23], v[170:171] op_sel_hi:[1,0]
	v_or_b32_e32 v34, 48, v146
	v_mad_i64_i32 v[34:35], s[10:11], v34, s22, 0
	v_lshl_add_u64 v[34:35], v[34:35], 1, s[16:17]
	v_lshl_add_u64 v[34:35], v[34:35], 0, v[148:149]
	v_cvt_pk_bf16_f32 v16, v22, v23
	v_cvt_pk_bf16_f32 v17, v24, v25
	global_store_dwordx4 v[34:35], v[14:17], off
	v_pk_mul_f32 v[22:23], v[80:81], v[170:171] op_sel_hi:[1,0]
	v_pk_mul_f32 v[24:25], v[78:79], v[170:171] op_sel_hi:[1,0]
	v_pk_mul_f32 v[14:15], v[70:71], v[170:171] op_sel_hi:[1,0]
	v_pk_mul_f32 v[16:17], v[72:73], v[170:171] op_sel_hi:[1,0]
	v_cvt_pk_bf16_f32 v14, v14, v15
	v_pk_mul_f32 v[10:11], v[10:11], v[150:151] op_sel_hi:[1,0]
	v_cvt_pk_bf16_f32 v15, v16, v17
	v_cvt_pk_bf16_f32 v16, v24, v25
	v_cvt_pk_bf16_f32 v17, v22, v23
	global_store_dwordx4 v[34:35], v[14:17], off offset:256
	v_pk_mul_f32 v[24:25], v[68:69], v[154:155] op_sel_hi:[1,0]
	v_pk_mul_f32 v[34:35], v[66:67], v[154:155] op_sel_hi:[1,0]
	v_add_u32_e32 v14, 0x80, v146
	v_mad_i64_i32 v[14:15], s[10:11], v14, s22, 0
	v_lshl_add_u64 v[14:15], v[14:15], 1, s[16:17]
	v_lshl_add_u64 v[22:23], v[14:15], 0, v[148:149]
	v_pk_mul_f32 v[14:15], v[54:55], v[154:155] op_sel_hi:[1,0]
	v_pk_mul_f32 v[16:17], v[56:57], v[154:155] op_sel_hi:[1,0]
	v_cvt_pk_bf16_f32 v14, v14, v15
	v_pk_mul_f32 v[12:13], v[12:13], v[150:151] op_sel_hi:[1,0]
	v_cvt_pk_bf16_f32 v15, v16, v17
	v_cvt_pk_bf16_f32 v16, v34, v35
	v_cvt_pk_bf16_f32 v17, v24, v25
	global_store_dwordx4 v[22:23], v[14:17], off
	v_pk_mul_f32 v[24:25], v[116:117], v[154:155] op_sel_hi:[1,0]
	v_pk_mul_f32 v[34:35], v[114:115], v[154:155] op_sel_hi:[1,0]
	v_pk_mul_f32 v[14:15], v[106:107], v[154:155] op_sel_hi:[1,0]
	v_pk_mul_f32 v[16:17], v[108:109], v[154:155] op_sel_hi:[1,0]
	v_cvt_pk_bf16_f32 v14, v14, v15
	v_rsq_f32_e32 v0, v0
	v_cvt_pk_bf16_f32 v15, v16, v17
	v_cvt_pk_bf16_f32 v16, v34, v35
	v_cvt_pk_bf16_f32 v17, v24, v25
	global_store_dwordx4 v[22:23], v[14:17], off offset:256
	v_pk_mul_f32 v[24:25], v[40:41], v[152:153] op_sel_hi:[1,0]
	v_pk_mul_f32 v[18:19], v[18:19], v[150:151] op_sel_hi:[1,0]
	v_add_u32_e32 v14, 0x90, v146
	v_mad_i64_i32 v[14:15], s[10:11], v14, s22, 0
	v_lshl_add_u64 v[14:15], v[14:15], 1, s[16:17]
	v_lshl_add_u64 v[22:23], v[14:15], 0, v[148:149]
	v_pk_mul_f32 v[14:15], v[30:31], v[152:153] op_sel_hi:[1,0]
	v_pk_mul_f32 v[16:17], v[32:33], v[152:153] op_sel_hi:[1,0]
	v_cvt_pk_bf16_f32 v14, v14, v15
	v_pk_mul_f32 v[30:31], v[38:39], v[152:153] op_sel_hi:[1,0]
	v_cvt_pk_bf16_f32 v15, v16, v17
	v_pk_mul_f32 v[4:5], v[4:5], v[0:1] op_sel_hi:[1,0]
	v_cvt_pk_bf16_f32 v16, v30, v31
	v_cvt_pk_bf16_f32 v17, v24, v25
	global_store_dwordx4 v[22:23], v[14:17], off
	v_pk_mul_f32 v[24:25], v[92:93], v[152:153] op_sel_hi:[1,0]
	v_pk_mul_f32 v[30:31], v[90:91], v[152:153] op_sel_hi:[1,0]
	v_pk_mul_f32 v[14:15], v[82:83], v[152:153] op_sel_hi:[1,0]
	v_pk_mul_f32 v[16:17], v[84:85], v[152:153] op_sel_hi:[1,0]
	v_cvt_pk_bf16_f32 v14, v14, v15
	v_pk_mul_f32 v[2:3], v[2:3], v[0:1] op_sel_hi:[1,0]
	v_cvt_pk_bf16_f32 v15, v16, v17
	v_cvt_pk_bf16_f32 v16, v30, v31
	v_cvt_pk_bf16_f32 v17, v24, v25
	global_store_dwordx4 v[22:23], v[14:17], off offset:256
	v_cvt_pk_bf16_f32 v10, v10, v11
	v_cvt_pk_bf16_f32 v11, v12, v13
	v_cvt_pk_bf16_f32 v12, v18, v19
	v_pk_mul_f32 v[18:19], v[58:59], v[150:151] op_sel_hi:[1,0]
	v_pk_mul_f32 v[8:9], v[8:9], v[0:1] op_sel_hi:[1,0]
	v_add_u32_e32 v14, 0xa0, v146
	v_mad_i64_i32 v[14:15], s[10:11], v14, s22, 0
	v_lshl_add_u64 v[14:15], v[14:15], 1, s[16:17]
	v_lshl_add_u64 v[14:15], v[14:15], 0, v[148:149]
	v_pk_mul_f32 v[16:17], v[20:21], v[150:151] op_sel_hi:[1,0]
	v_pk_mul_f32 v[6:7], v[6:7], v[0:1] op_sel_hi:[1,0]
	v_cvt_pk_bf16_f32 v13, v16, v17
	global_store_dwordx4 v[14:15], v[10:13], off
	v_pk_mul_f32 v[16:17], v[60:61], v[150:151] op_sel_hi:[1,0]
	s_andn2_b64 vcc, exec, s[4:5]
	v_pk_mul_f32 v[10:11], v[46:47], v[150:151] op_sel_hi:[1,0]
	v_pk_mul_f32 v[12:13], v[48:49], v[150:151] op_sel_hi:[1,0]
	v_cvt_pk_bf16_f32 v10, v10, v11
	s_mov_b64 s[4:5], -1
	v_cvt_pk_bf16_f32 v11, v12, v13
	v_cvt_pk_bf16_f32 v12, v18, v19
	v_cvt_pk_bf16_f32 v13, v16, v17
	global_store_dwordx4 v[14:15], v[10:13], off offset:256
	v_cvt_pk_bf16_f32 v2, v2, v3
	v_cvt_pk_bf16_f32 v3, v4, v5
	v_cvt_pk_bf16_f32 v4, v6, v7
	v_cvt_pk_bf16_f32 v5, v8, v9
	v_pk_mul_f32 v[6:7], v[52:53], v[0:1] op_sel_hi:[1,0]
	s_nop 0
	v_add_u32_e32 v10, 0xb0, v146
	v_mad_i64_i32 v[10:11], s[10:11], v10, s22, 0
	v_lshl_add_u64 v[10:11], v[10:11], 1, s[16:17]
	v_lshl_add_u64 v[10:11], v[10:11], 0, v[148:149]
	global_store_dwordx4 v[10:11], v[2:5], off
	v_pk_mul_f32 v[8:9], v[50:51], v[0:1] op_sel_hi:[1,0]
	s_nop 0
	v_pk_mul_f32 v[4:5], v[28:29], v[0:1] op_sel_hi:[1,0]
	v_pk_mul_f32 v[2:3], v[26:27], v[0:1] op_sel_hi:[1,0]
	s_nop 0
	v_cvt_pk_bf16_f32 v2, v2, v3
	v_cvt_pk_bf16_f32 v3, v4, v5
	v_cvt_pk_bf16_f32 v4, v8, v9
	v_cvt_pk_bf16_f32 v5, v6, v7
	global_store_dwordx4 v[10:11], v[2:5], off offset:256
	s_cbranch_vccnz .LBB0_158
	s_nop 0
	v_mov_b32_e32 v2, v1
	v_mov_b32_e32 v3, v1
	v_mov_b32_e32 v0, v1
	v_mov_b64_e32 v[52:53], v[2:3]
	v_mov_b64_e32 v[50:51], v[0:1]
	s_andn2_b64 vcc, exec, s[14:15]
	s_cbranch_vccnz .LBB0_157
	s_barrier
	s_branch .LBB0_157

.LBB0_369:
	s_xor_b64 s[12:13], s[8:9], -1
	s_andn2_b64 vcc, exec, s[10:11]
	s_cbranch_vccnz .LBB0_407
	v_mov_b32_e32 v2, v1
	v_mov_b32_e32 v3, v1
	v_mov_b32_e32 v0, v1
	v_mov_b64_e32 v[8:9], v[2:3]
	v_mov_b64_e32 v[6:7], v[0:1]
	s_add_u32 s8, s6, s2
	s_addc_u32 s9, s7, s1
	s_nop 0
	s_add_u32 s8, s8, s14
	s_addc_u32 s9, s9, 0
	s_nop 0
	s_ashr_i32 s24, s21, 6
	s_lshl_b32 s10, s24, 3
	s_nop 0
	v_bfe_u32 v10, v4, 3, 3
	v_or_b32_e32 v12, s10, v10
	s_nop 0
	v_lshrrev_b32_e32 v13, 1, v12
	v_and_b32_e32 v5, 63, v4
	s_nop 0
	v_xor_b32_e32 v13, v13, v4
	s_lshl_b32 s11, s24, 1
	s_nop 0
	v_bfe_u32 v11, v5, 3, 2
	v_lshlrev_b32_e32 v13, 3, v13
	s_nop 0
	v_lshlrev_b32_e32 v14, 1, v12
	v_and_or_b32 v11, s11, 4, v11
	s_nop 0
	v_and_b32_e32 v13, 56, v13
	s_and_b32 s11, s10, 0x7fffffe0
	s_nop 0
	v_and_b32_e32 v14, 24, v14
	v_mul_lo_u32 v12, v12, s20
	s_nop 0
	v_or3_b32 v14, s11, v14, v11
	v_or_b32_e32 v12, v13, v12
	s_nop 0
	v_lshlrev_b32_e32 v204, 1, v12
	v_mul_lo_u32 v12, v14, s20
	s_nop 0
	s_add_i32 s10, s10, 64
	v_or_b32_e32 v12, v12, v13
	s_nop 0
	v_or_b32_e32 v10, s10, v10
	v_lshlrev_b32_e32 v205, 1, v12
	s_nop 0
	v_lshrrev_b32_e32 v12, 1, v10
	v_xor_b32_e32 v12, v12, v4
	s_nop 0
	v_lshlrev_b32_e32 v12, 3, v12
	v_lshlrev_b32_e32 v13, 1, v10
	s_nop 0
	v_and_b32_e32 v12, 56, v12
	s_and_b32 s10, s10, 0x7fffffe0
	s_nop 0
	v_and_b32_e32 v13, 24, v13
	v_mul_lo_u32 v10, v10, s20
	s_nop 0
	s_lshl_b32 s14, s24, 10
	v_or3_b32 v11, s10, v13, v11
	s_nop 0
	v_or_b32_e32 v10, v12, v10
	s_add_i32 s31, s14, 0
	s_nop 0
	v_lshlrev_b32_e32 v206, 1, v10
	v_mul_lo_u32 v10, v11, s20
	s_nop 0
	s_lshl_b32 s30, s20, 9
	s_add_i32 s34, s31, 0x10000
	s_nop 0
	v_or_b32_e32 v10, v10, v12
	s_and_b32 s9, s9, 0xffff
	s_nop 0
	s_mov_b32 s10, s50
	s_mov_b32 s11, s51
	s_nop 0
	s_mul_i32 s65, s23, s30
	s_mov_b32 m0, s34
	s_nop 0
	s_add_i32 s35, s31, 0x12000
	v_lshlrev_b32_e32 v207, 1, v10
	s_nop 0
	s_lshl_b32 s29, s20, 8
	s_add_i32 s36, s31, 0x14000
	s_nop 0
	s_add_i32 s46, s65, s29
	s_add_i32 s37, s31, 0x16000
	s_nop 0
	s_and_b32 s49, s49, 0xffff
	s_mul_i32 s64, s22, s30
	s_nop 0
	s_add_i32 s38, s31, 0x2000
	s_add_i32 s39, s31, 0x4000
	s_nop 0
	s_add_i32 s40, s31, 0x6000
	s_ashr_i32 s25, s21, 8
	s_nop 0
	buffer_load_dwordx4 v205, s[8:11], s65 offen lds
	s_mov_b32 m0, s35
	s_nop 0
	buffer_load_dwordx4 v207, s[8:11], s65 offen lds
	s_mov_b32 m0, s36
	s_nop 0
	buffer_load_dwordx4 v205, s[8:11], s46 offen lds
	s_mov_b32 m0, s37
	s_nop 0
	buffer_load_dwordx4 v207, s[8:11], s46 offen lds
	s_mov_b32 m0, s31
	s_add_i32 s10, s64, s29
	buffer_load_dwordx4 v204, s[48:51], s64 offen lds
	s_mov_b32 m0, s38
	s_cmp_eq_u32 s25, 1
	buffer_load_dwordx4 v206, s[48:51], s64 offen lds
	s_mov_b32 m0, s39
	s_cselect_b64 s[14:15], -1, 0
	buffer_load_dwordx4 v204, s[48:51], s10 offen lds
	s_mov_b32 m0, s40
	s_cmp_lg_u32 s25, 1
	buffer_load_dwordx4 v206, s[48:51], s10 offen lds
	s_cbranch_scc1 .LBB0_372
	s_barrier

.Lc0r_first:
	s_add_i32 s81, s64, 0x80
	s_and_b64 s[10:11], s[10:11], exec
	s_cselect_b32 s84, s24, s81
	s_cselect_b32 s85, s25, s65
	s_add_i32 s10, 0, 0x10000
	v_add_u32_e32 v3, s10, v208
	v_add_u32_e32 v144, s10, v209
	s_add_i32 s10, 0, 0x14000
	ds_read_b128 v[116:119], v3
	ds_read_b128 v[120:123], v3 offset:2048
	ds_read_b128 v[140:143], v144
	ds_read_b128 v[144:147], v144 offset:2048
	v_add_u32_e32 v3, s10, v208
	v_add_u32_e32 v176, s10, v209
	ds_read_b128 v[164:167], v3
	ds_read_b128 v[168:171], v3 offset:2048
	ds_read_b128 v[172:175], v176
	ds_read_b128 v[176:179], v176 offset:2048
	s_add_i32 s81, s84, 0x80
	s_add_i32 s82, s85, 0x80
	s_add_i32 s10, s29, s64
	s_mov_b32 m0, s53
	ds_read_b128 v[180:183], v214
	ds_read_b128 v[184:187], v214 offset:2048
	ds_read_b128 v[188:191], v215
	ds_read_b128 v[192:195], v215 offset:2048
	ds_read_b128 v[196:199], v214 offset:4096
	ds_read_b128 v[216:219], v214 offset:6144
	ds_read_b128 v[220:223], v215 offset:4096
	ds_read_b128 v[224:227], v215 offset:6144
	buffer_load_dwordx4 v204, s[48:51], s10 offen lds
	s_mov_b32 m0, s54
	s_nop 0
	buffer_load_dwordx4 v206, s[48:51], s10 offen lds
	s_waitcnt vmcnt(8)
	s_waitcnt lgkmcnt(0)
	s_barrier
	s_setprio 1
	s_waitcnt lgkmcnt(0)
	v_mfma_f32_16x16x32_bf16 v[160:163], v[116:119], v[180:183], 0
	v_mfma_f32_16x16x32_bf16 v[152:155], v[120:123], v[180:183], 0
	v_mfma_f32_16x16x32_bf16 v[132:135], v[116:119], v[184:187], 0
	v_mfma_f32_16x16x32_bf16 v[124:127], v[120:123], v[184:187], 0
	v_mfma_f32_16x16x32_bf16 v[108:111], v[116:119], v[196:199], 0
	v_mfma_f32_16x16x32_bf16 v[100:103], v[120:123], v[196:199], 0
	v_mfma_f32_16x16x32_bf16 v[92:95], v[116:119], v[216:219], 0
	v_mfma_f32_16x16x32_bf16 v[84:87], v[120:123], v[216:219], 0
	v_mfma_f32_16x16x32_bf16 v[160:163], v[140:143], v[188:191], v[160:163]
	v_mfma_f32_16x16x32_bf16 v[152:155], v[144:147], v[188:191], v[152:155]
	v_mfma_f32_16x16x32_bf16 v[132:135], v[140:143], v[192:195], v[132:135]
	v_mfma_f32_16x16x32_bf16 v[124:127], v[144:147], v[192:195], v[124:127]
	v_mfma_f32_16x16x32_bf16 v[108:111], v[140:143], v[220:223], v[108:111]
	v_mfma_f32_16x16x32_bf16 v[100:103], v[144:147], v[220:223], v[100:103]
	v_mfma_f32_16x16x32_bf16 v[92:95], v[140:143], v[224:227], v[92:95]
	v_mfma_f32_16x16x32_bf16 v[84:87], v[144:147], v[224:227], v[84:87]
	s_setprio 0
	s_setprio 1
	v_mfma_f32_16x16x32_bf16 v[156:159], v[164:167], v[180:183], 0
	v_mfma_f32_16x16x32_bf16 v[148:151], v[168:171], v[180:183], 0
	v_mfma_f32_16x16x32_bf16 v[136:139], v[164:167], v[184:187], 0
	v_mfma_f32_16x16x32_bf16 v[128:131], v[168:171], v[184:187], 0
	v_mfma_f32_16x16x32_bf16 v[112:115], v[164:167], v[196:199], 0
	v_mfma_f32_16x16x32_bf16 v[104:107], v[168:171], v[196:199], 0
	v_mfma_f32_16x16x32_bf16 v[96:99], v[164:167], v[216:219], 0
	v_mfma_f32_16x16x32_bf16 v[88:91], v[168:171], v[216:219], 0
	v_mfma_f32_16x16x32_bf16 v[156:159], v[172:175], v[188:191], v[156:159]
	v_mfma_f32_16x16x32_bf16 v[148:151], v[176:179], v[188:191], v[148:151]
	v_mfma_f32_16x16x32_bf16 v[136:139], v[172:175], v[192:195], v[136:139]
	v_mfma_f32_16x16x32_bf16 v[128:131], v[176:179], v[192:195], v[128:131]
	v_mfma_f32_16x16x32_bf16 v[112:115], v[172:175], v[220:223], v[112:115]
	v_mfma_f32_16x16x32_bf16 v[104:107], v[176:179], v[220:223], v[104:107]
	v_mfma_f32_16x16x32_bf16 v[96:99], v[172:175], v[224:227], v[96:99]
	v_mfma_f32_16x16x32_bf16 v[88:91], v[176:179], v[224:227], v[88:91]
	s_setprio 0
	s_barrier
	s_mov_b32 m0, s34
	s_mov_b32 s10, s50
	s_mov_b32 s11, s51
	ds_read_b128 v[180:183], v214 offset:16384
	ds_read_b128 v[184:187], v214 offset:18432
	ds_read_b128 v[188:191], v215 offset:16384
	ds_read_b128 v[192:195], v215 offset:18432
	ds_read_b128 v[196:199], v214 offset:20480
	ds_read_b128 v[216:219], v214 offset:22528
	ds_read_b128 v[220:223], v215 offset:20480
	ds_read_b128 v[224:227], v215 offset:22528
	buffer_load_dwordx4 v205, s[8:11], s85 offen lds
	s_mov_b32 m0, s35
	s_nop 0
	buffer_load_dwordx4 v207, s[8:11], s85 offen lds
	s_add_i32 s85, s85, s29
	s_mov_b32 m0, s36
	s_nop 0
	buffer_load_dwordx4 v205, s[8:11], s85 offen lds
	s_mov_b32 m0, s37
	s_nop 0
	buffer_load_dwordx4 v207, s[8:11], s85 offen lds
	s_mov_b32 m0, s31
	s_nop 0
	buffer_load_dwordx4 v204, s[48:51], s84 offen lds
	s_mov_b32 m0, s38
	s_nop 0
	buffer_load_dwordx4 v206, s[48:51], s84 offen lds
	s_waitcnt vmcnt(8)
	s_waitcnt lgkmcnt(0)
	s_barrier
	s_setprio 1
	s_waitcnt lgkmcnt(0)
	v_mfma_f32_16x16x32_bf16 v[76:79], v[116:119], v[180:183], 0
	v_mfma_f32_16x16x32_bf16 v[68:71], v[120:123], v[180:183], 0
	v_mfma_f32_16x16x32_bf16 v[60:63], v[116:119], v[184:187], 0
	v_mfma_f32_16x16x32_bf16 v[52:55], v[120:123], v[184:187], 0
	v_mfma_f32_16x16x32_bf16 v[44:47], v[116:119], v[196:199], 0
	v_mfma_f32_16x16x32_bf16 v[36:39], v[120:123], v[196:199], 0
	v_mfma_f32_16x16x32_bf16 v[24:27], v[116:119], v[216:219], 0
	v_mfma_f32_16x16x32_bf16 v[20:23], v[120:123], v[216:219], 0
	v_mfma_f32_16x16x32_bf16 v[76:79], v[140:143], v[188:191], v[76:79]
	v_mfma_f32_16x16x32_bf16 v[68:71], v[144:147], v[188:191], v[68:71]
	v_mfma_f32_16x16x32_bf16 v[60:63], v[140:143], v[192:195], v[60:63]
	v_mfma_f32_16x16x32_bf16 v[52:55], v[144:147], v[192:195], v[52:55]
	v_mfma_f32_16x16x32_bf16 v[44:47], v[140:143], v[220:223], v[44:47]
	v_mfma_f32_16x16x32_bf16 v[36:39], v[144:147], v[220:223], v[36:39]
	v_mfma_f32_16x16x32_bf16 v[24:27], v[140:143], v[224:227], v[24:27]
	v_mfma_f32_16x16x32_bf16 v[20:23], v[144:147], v[224:227], v[20:23]
	s_setprio 0
	s_setprio 1
	v_mfma_f32_16x16x32_bf16 v[80:83], v[164:167], v[180:183], 0
	v_mfma_f32_16x16x32_bf16 v[72:75], v[168:171], v[180:183], 0
	v_mfma_f32_16x16x32_bf16 v[64:67], v[164:167], v[184:187], 0
	v_mfma_f32_16x16x32_bf16 v[56:59], v[168:171], v[184:187], 0
	v_mfma_f32_16x16x32_bf16 v[48:51], v[164:167], v[196:199], 0
	v_mfma_f32_16x16x32_bf16 v[40:43], v[168:171], v[196:199], 0
	v_mfma_f32_16x16x32_bf16 v[28:31], v[164:167], v[216:219], 0
	v_mfma_f32_16x16x32_bf16 v[32:35], v[168:171], v[216:219], 0
	v_mfma_f32_16x16x32_bf16 v[80:83], v[172:175], v[188:191], v[80:83]
	v_mfma_f32_16x16x32_bf16 v[72:75], v[176:179], v[188:191], v[72:75]
	v_mfma_f32_16x16x32_bf16 v[64:67], v[172:175], v[192:195], v[64:67]
	v_mfma_f32_16x16x32_bf16 v[56:59], v[176:179], v[192:195], v[56:59]
	v_mfma_f32_16x16x32_bf16 v[48:51], v[172:175], v[220:223], v[48:51]
	v_mfma_f32_16x16x32_bf16 v[40:43], v[176:179], v[220:223], v[40:43]
	v_mfma_f32_16x16x32_bf16 v[28:31], v[172:175], v[224:227], v[28:31]
	v_mfma_f32_16x16x32_bf16 v[32:35], v[176:179], v[224:227], v[32:35]
	s_setprio 0
	s_barrier
	s_add_i32 s85, 0, 0x18000
	v_add_u32_e32 v3, s85, v208
	v_add_u32_e32 v144, s85, v209
	s_add_i32 s85, 0, 0x1c000
	ds_read_b128 v[116:119], v3
	ds_read_b128 v[120:123], v3 offset:2048
	ds_read_b128 v[140:143], v144
	ds_read_b128 v[144:147], v144 offset:2048
	v_add_u32_e32 v3, s85, v208
	v_add_u32_e32 v176, s85, v209
	ds_read_b128 v[164:167], v3
	ds_read_b128 v[168:171], v3 offset:2048
	ds_read_b128 v[172:175], v176
	ds_read_b128 v[176:179], v176 offset:2048
	s_add_i32 s84, s84, s29
	s_mov_b32 m0, s39
	ds_read_b128 v[180:183], v214 offset:32768
	ds_read_b128 v[184:187], v214 offset:34816
	ds_read_b128 v[188:191], v215 offset:32768
	ds_read_b128 v[192:195], v215 offset:34816
	ds_read_b128 v[196:199], v214 offset:36864
	ds_read_b128 v[216:219], v214 offset:38912
	ds_read_b128 v[220:223], v215 offset:36864
	ds_read_b128 v[224:227], v215 offset:38912
	buffer_load_dwordx4 v204, s[48:51], s84 offen lds
	s_mov_b32 m0, s40
	s_nop 0
	buffer_load_dwordx4 v206, s[48:51], s84 offen lds
	s_waitcnt vmcnt(8)
	s_waitcnt lgkmcnt(0)
	s_barrier
	s_setprio 1
	s_waitcnt lgkmcnt(0)
	v_mfma_f32_16x16x32_bf16 v[160:163], v[116:119], v[180:183], v[160:163]
	v_mfma_f32_16x16x32_bf16 v[152:155], v[120:123], v[180:183], v[152:155]
	v_mfma_f32_16x16x32_bf16 v[132:135], v[116:119], v[184:187], v[132:135]
	v_mfma_f32_16x16x32_bf16 v[124:127], v[120:123], v[184:187], v[124:127]
	v_mfma_f32_16x16x32_bf16 v[108:111], v[116:119], v[196:199], v[108:111]
	v_mfma_f32_16x16x32_bf16 v[100:103], v[120:123], v[196:199], v[100:103]
	v_mfma_f32_16x16x32_bf16 v[92:95], v[116:119], v[216:219], v[92:95]
	v_mfma_f32_16x16x32_bf16 v[84:87], v[120:123], v[216:219], v[84:87]
	v_mfma_f32_16x16x32_bf16 v[160:163], v[140:143], v[188:191], v[160:163]
	v_mfma_f32_16x16x32_bf16 v[152:155], v[144:147], v[188:191], v[152:155]
	v_mfma_f32_16x16x32_bf16 v[132:135], v[140:143], v[192:195], v[132:135]
	v_mfma_f32_16x16x32_bf16 v[124:127], v[144:147], v[192:195], v[124:127]
	v_mfma_f32_16x16x32_bf16 v[108:111], v[140:143], v[220:223], v[108:111]
	v_mfma_f32_16x16x32_bf16 v[100:103], v[144:147], v[220:223], v[100:103]
	v_mfma_f32_16x16x32_bf16 v[92:95], v[140:143], v[224:227], v[92:95]
	v_mfma_f32_16x16x32_bf16 v[84:87], v[144:147], v[224:227], v[84:87]
	s_setprio 0
	s_setprio 1
	v_mfma_f32_16x16x32_bf16 v[156:159], v[164:167], v[180:183], v[156:159]
	v_mfma_f32_16x16x32_bf16 v[148:151], v[168:171], v[180:183], v[148:151]
	v_mfma_f32_16x16x32_bf16 v[136:139], v[164:167], v[184:187], v[136:139]
	v_mfma_f32_16x16x32_bf16 v[128:131], v[168:171], v[184:187], v[128:131]
	v_mfma_f32_16x16x32_bf16 v[112:115], v[164:167], v[196:199], v[112:115]
	v_mfma_f32_16x16x32_bf16 v[104:107], v[168:171], v[196:199], v[104:107]
	v_mfma_f32_16x16x32_bf16 v[96:99], v[164:167], v[216:219], v[96:99]
	v_mfma_f32_16x16x32_bf16 v[88:91], v[168:171], v[216:219], v[88:91]
	v_mfma_f32_16x16x32_bf16 v[156:159], v[172:175], v[188:191], v[156:159]
	v_mfma_f32_16x16x32_bf16 v[148:151], v[176:179], v[188:191], v[148:151]
	v_mfma_f32_16x16x32_bf16 v[136:139], v[172:175], v[192:195], v[136:139]
	v_mfma_f32_16x16x32_bf16 v[128:131], v[176:179], v[192:195], v[128:131]
	v_mfma_f32_16x16x32_bf16 v[112:115], v[172:175], v[220:223], v[112:115]
	v_mfma_f32_16x16x32_bf16 v[104:107], v[176:179], v[220:223], v[104:107]
	v_mfma_f32_16x16x32_bf16 v[96:99], v[172:175], v[224:227], v[96:99]
	v_mfma_f32_16x16x32_bf16 v[88:91], v[176:179], v[224:227], v[88:91]
	s_setprio 0
	s_barrier
	s_mov_b32 m0, s41
	ds_read_b128 v[180:183], v214 offset:49152
	ds_read_b128 v[184:187], v214 offset:51200
	ds_read_b128 v[188:191], v215 offset:49152
	ds_read_b128 v[192:195], v215 offset:51200
	ds_read_b128 v[196:199], v214 offset:53248
	ds_read_b128 v[216:219], v214 offset:55296
	ds_read_b128 v[220:223], v215 offset:53248
	ds_read_b128 v[224:227], v215 offset:55296
	buffer_load_dwordx4 v205, s[8:11], s82 offen lds
	s_mov_b32 m0, s42
	s_nop 0
	buffer_load_dwordx4 v207, s[8:11], s82 offen lds
	s_add_i32 s82, s82, s29
	s_mov_b32 m0, s45
	s_nop 0
	buffer_load_dwordx4 v205, s[8:11], s82 offen lds
	s_mov_b32 m0, s46
	s_nop 0
	buffer_load_dwordx4 v207, s[8:11], s82 offen lds
	s_mov_b32 m0, s43
	s_nop 0
	buffer_load_dwordx4 v204, s[48:51], s81 offen lds
	s_mov_b32 m0, s44
	s_nop 0
	buffer_load_dwordx4 v206, s[48:51], s81 offen lds
	s_waitcnt vmcnt(8)
	s_waitcnt lgkmcnt(0)
	s_barrier
	s_setprio 1
	s_waitcnt lgkmcnt(0)
	v_mfma_f32_16x16x32_bf16 v[76:79], v[116:119], v[180:183], v[76:79]
	v_mfma_f32_16x16x32_bf16 v[68:71], v[120:123], v[180:183], v[68:71]
	v_mfma_f32_16x16x32_bf16 v[60:63], v[116:119], v[184:187], v[60:63]
	v_mfma_f32_16x16x32_bf16 v[52:55], v[120:123], v[184:187], v[52:55]
	v_mfma_f32_16x16x32_bf16 v[44:47], v[116:119], v[196:199], v[44:47]
	v_mfma_f32_16x16x32_bf16 v[36:39], v[120:123], v[196:199], v[36:39]
	v_mfma_f32_16x16x32_bf16 v[24:27], v[116:119], v[216:219], v[24:27]
	v_mfma_f32_16x16x32_bf16 v[20:23], v[120:123], v[216:219], v[20:23]
	v_mfma_f32_16x16x32_bf16 v[76:79], v[140:143], v[188:191], v[76:79]
	v_mfma_f32_16x16x32_bf16 v[68:71], v[144:147], v[188:191], v[68:71]
	v_mfma_f32_16x16x32_bf16 v[60:63], v[140:143], v[192:195], v[60:63]
	v_mfma_f32_16x16x32_bf16 v[52:55], v[144:147], v[192:195], v[52:55]
	v_mfma_f32_16x16x32_bf16 v[44:47], v[140:143], v[220:223], v[44:47]
	v_mfma_f32_16x16x32_bf16 v[36:39], v[144:147], v[220:223], v[36:39]
	v_mfma_f32_16x16x32_bf16 v[24:27], v[140:143], v[224:227], v[24:27]
	v_mfma_f32_16x16x32_bf16 v[20:23], v[144:147], v[224:227], v[20:23]
	s_setprio 0
	s_setprio 1
	v_mfma_f32_16x16x32_bf16 v[80:83], v[164:167], v[180:183], v[80:83]
	v_mfma_f32_16x16x32_bf16 v[72:75], v[168:171], v[180:183], v[72:75]
	v_mfma_f32_16x16x32_bf16 v[64:67], v[164:167], v[184:187], v[64:67]
	v_mfma_f32_16x16x32_bf16 v[56:59], v[168:171], v[184:187], v[56:59]
	v_mfma_f32_16x16x32_bf16 v[48:51], v[164:167], v[196:199], v[48:51]
	v_mfma_f32_16x16x32_bf16 v[40:43], v[168:171], v[196:199], v[40:43]
	v_mfma_f32_16x16x32_bf16 v[28:31], v[164:167], v[216:219], v[28:31]
	v_mfma_f32_16x16x32_bf16 v[32:35], v[168:171], v[216:219], v[32:35]
	v_mfma_f32_16x16x32_bf16 v[80:83], v[172:175], v[188:191], v[80:83]
	v_mfma_f32_16x16x32_bf16 v[72:75], v[176:179], v[188:191], v[72:75]
	v_mfma_f32_16x16x32_bf16 v[64:67], v[172:175], v[192:195], v[64:67]
	v_mfma_f32_16x16x32_bf16 v[56:59], v[176:179], v[192:195], v[56:59]
	v_mfma_f32_16x16x32_bf16 v[48:51], v[172:175], v[220:223], v[48:51]
	v_mfma_f32_16x16x32_bf16 v[40:43], v[176:179], v[220:223], v[40:43]
	v_mfma_f32_16x16x32_bf16 v[28:31], v[172:175], v[224:227], v[28:31]
	v_mfma_f32_16x16x32_bf16 v[32:35], v[176:179], v[224:227], v[32:35]
	s_setprio 0
	s_barrier
	s_branch .Lc0r_tail
.LBB0_382:
	s_cmp_eq_u32 s78, 0
	s_cbranch_scc1 .Lc0r_first
	s_add_i32 s81, s64, 0x80
	s_and_b64 s[10:11], s[10:11], exec
	s_cselect_b32 s84, s24, s81
	s_cselect_b32 s85, s25, s65
	s_add_i32 s10, 0, 0x10000
	v_add_u32_e32 v3, s10, v208
	v_add_u32_e32 v144, s10, v209
	s_add_i32 s10, 0, 0x14000
	ds_read_b128 v[116:119], v3
	ds_read_b128 v[120:123], v3 offset:2048
	ds_read_b128 v[140:143], v144
	ds_read_b128 v[144:147], v144 offset:2048
	v_add_u32_e32 v3, s10, v208
	v_add_u32_e32 v176, s10, v209
	ds_read_b128 v[164:167], v3
	ds_read_b128 v[168:171], v3 offset:2048
	ds_read_b128 v[172:175], v176
	ds_read_b128 v[176:179], v176 offset:2048
	s_add_i32 s81, s84, 0x80
	s_add_i32 s82, s85, 0x80
	s_add_i32 s10, s29, s64
	s_mov_b32 m0, s53
	ds_read_b128 v[180:183], v214
	ds_read_b128 v[184:187], v214 offset:2048
	ds_read_b128 v[188:191], v215
	ds_read_b128 v[192:195], v215 offset:2048
	ds_read_b128 v[196:199], v214 offset:4096
	ds_read_b128 v[216:219], v214 offset:6144
	ds_read_b128 v[220:223], v215 offset:4096
	ds_read_b128 v[224:227], v215 offset:6144
	buffer_load_dwordx4 v204, s[48:51], s10 offen lds
	s_mov_b32 m0, s54
	s_nop 0
	buffer_load_dwordx4 v206, s[48:51], s10 offen lds
	s_waitcnt vmcnt(8)
	s_waitcnt lgkmcnt(0)
	s_barrier
	s_setprio 1
	s_waitcnt lgkmcnt(0)
	v_mfma_f32_16x16x32_bf16 v[160:163], v[116:119], v[180:183], v[160:163]
	v_mfma_f32_16x16x32_bf16 v[152:155], v[120:123], v[180:183], v[152:155]
	v_mfma_f32_16x16x32_bf16 v[132:135], v[116:119], v[184:187], v[132:135]
	v_mfma_f32_16x16x32_bf16 v[124:127], v[120:123], v[184:187], v[124:127]
	v_mfma_f32_16x16x32_bf16 v[108:111], v[116:119], v[196:199], v[108:111]
	v_mfma_f32_16x16x32_bf16 v[100:103], v[120:123], v[196:199], v[100:103]
	v_mfma_f32_16x16x32_bf16 v[92:95], v[116:119], v[216:219], v[92:95]
	v_mfma_f32_16x16x32_bf16 v[84:87], v[120:123], v[216:219], v[84:87]
	v_mfma_f32_16x16x32_bf16 v[160:163], v[140:143], v[188:191], v[160:163]
	v_mfma_f32_16x16x32_bf16 v[152:155], v[144:147], v[188:191], v[152:155]
	v_mfma_f32_16x16x32_bf16 v[132:135], v[140:143], v[192:195], v[132:135]
	v_mfma_f32_16x16x32_bf16 v[124:127], v[144:147], v[192:195], v[124:127]
	v_mfma_f32_16x16x32_bf16 v[108:111], v[140:143], v[220:223], v[108:111]
	v_mfma_f32_16x16x32_bf16 v[100:103], v[144:147], v[220:223], v[100:103]
	v_mfma_f32_16x16x32_bf16 v[92:95], v[140:143], v[224:227], v[92:95]
	v_mfma_f32_16x16x32_bf16 v[84:87], v[144:147], v[224:227], v[84:87]
	s_setprio 0
	s_setprio 1
	v_mfma_f32_16x16x32_bf16 v[156:159], v[164:167], v[180:183], v[156:159]
	v_mfma_f32_16x16x32_bf16 v[148:151], v[168:171], v[180:183], v[148:151]
	v_mfma_f32_16x16x32_bf16 v[136:139], v[164:167], v[184:187], v[136:139]
	v_mfma_f32_16x16x32_bf16 v[128:131], v[168:171], v[184:187], v[128:131]
	v_mfma_f32_16x16x32_bf16 v[112:115], v[164:167], v[196:199], v[112:115]
	v_mfma_f32_16x16x32_bf16 v[104:107], v[168:171], v[196:199], v[104:107]
	v_mfma_f32_16x16x32_bf16 v[96:99], v[164:167], v[216:219], v[96:99]
	v_mfma_f32_16x16x32_bf16 v[88:91], v[168:171], v[216:219], v[88:91]
	v_mfma_f32_16x16x32_bf16 v[156:159], v[172:175], v[188:191], v[156:159]
	v_mfma_f32_16x16x32_bf16 v[148:151], v[176:179], v[188:191], v[148:151]
	v_mfma_f32_16x16x32_bf16 v[136:139], v[172:175], v[192:195], v[136:139]
	v_mfma_f32_16x16x32_bf16 v[128:131], v[176:179], v[192:195], v[128:131]
	v_mfma_f32_16x16x32_bf16 v[112:115], v[172:175], v[220:223], v[112:115]
	v_mfma_f32_16x16x32_bf16 v[104:107], v[176:179], v[220:223], v[104:107]
	v_mfma_f32_16x16x32_bf16 v[96:99], v[172:175], v[224:227], v[96:99]
	v_mfma_f32_16x16x32_bf16 v[88:91], v[176:179], v[224:227], v[88:91]
	s_setprio 0
	s_barrier
	s_mov_b32 m0, s34
	s_mov_b32 s10, s50
	s_mov_b32 s11, s51
	ds_read_b128 v[180:183], v214 offset:16384
	ds_read_b128 v[184:187], v214 offset:18432
	ds_read_b128 v[188:191], v215 offset:16384
	ds_read_b128 v[192:195], v215 offset:18432
	ds_read_b128 v[196:199], v214 offset:20480
	ds_read_b128 v[216:219], v214 offset:22528
	ds_read_b128 v[220:223], v215 offset:20480
	ds_read_b128 v[224:227], v215 offset:22528
	buffer_load_dwordx4 v205, s[8:11], s85 offen lds
	s_mov_b32 m0, s35
	s_nop 0
	buffer_load_dwordx4 v207, s[8:11], s85 offen lds
	s_add_i32 s85, s85, s29
	s_mov_b32 m0, s36
	s_nop 0
	buffer_load_dwordx4 v205, s[8:11], s85 offen lds
	s_mov_b32 m0, s37
	s_nop 0
	buffer_load_dwordx4 v207, s[8:11], s85 offen lds
	s_mov_b32 m0, s31
	s_nop 0
	buffer_load_dwordx4 v204, s[48:51], s84 offen lds
	s_mov_b32 m0, s38
	s_nop 0
	buffer_load_dwordx4 v206, s[48:51], s84 offen lds
	s_waitcnt vmcnt(8)
	s_waitcnt lgkmcnt(0)
	s_barrier
	s_setprio 1
	s_waitcnt lgkmcnt(0)
	v_mfma_f32_16x16x32_bf16 v[76:79], v[116:119], v[180:183], v[76:79]
	v_mfma_f32_16x16x32_bf16 v[68:71], v[120:123], v[180:183], v[68:71]
	v_mfma_f32_16x16x32_bf16 v[60:63], v[116:119], v[184:187], v[60:63]
	v_mfma_f32_16x16x32_bf16 v[52:55], v[120:123], v[184:187], v[52:55]
	v_mfma_f32_16x16x32_bf16 v[44:47], v[116:119], v[196:199], v[44:47]
	v_mfma_f32_16x16x32_bf16 v[36:39], v[120:123], v[196:199], v[36:39]
	v_mfma_f32_16x16x32_bf16 v[24:27], v[116:119], v[216:219], v[24:27]
	v_mfma_f32_16x16x32_bf16 v[20:23], v[120:123], v[216:219], v[20:23]
	v_mfma_f32_16x16x32_bf16 v[76:79], v[140:143], v[188:191], v[76:79]
	v_mfma_f32_16x16x32_bf16 v[68:71], v[144:147], v[188:191], v[68:71]
	v_mfma_f32_16x16x32_bf16 v[60:63], v[140:143], v[192:195], v[60:63]
	v_mfma_f32_16x16x32_bf16 v[52:55], v[144:147], v[192:195], v[52:55]
	v_mfma_f32_16x16x32_bf16 v[44:47], v[140:143], v[220:223], v[44:47]
	v_mfma_f32_16x16x32_bf16 v[36:39], v[144:147], v[220:223], v[36:39]
	v_mfma_f32_16x16x32_bf16 v[24:27], v[140:143], v[224:227], v[24:27]
	v_mfma_f32_16x16x32_bf16 v[20:23], v[144:147], v[224:227], v[20:23]
	s_setprio 0
	s_setprio 1
	v_mfma_f32_16x16x32_bf16 v[80:83], v[164:167], v[180:183], v[80:83]
	v_mfma_f32_16x16x32_bf16 v[72:75], v[168:171], v[180:183], v[72:75]
	v_mfma_f32_16x16x32_bf16 v[64:67], v[164:167], v[184:187], v[64:67]
	v_mfma_f32_16x16x32_bf16 v[56:59], v[168:171], v[184:187], v[56:59]
	v_mfma_f32_16x16x32_bf16 v[48:51], v[164:167], v[196:199], v[48:51]
	v_mfma_f32_16x16x32_bf16 v[40:43], v[168:171], v[196:199], v[40:43]
	v_mfma_f32_16x16x32_bf16 v[28:31], v[164:167], v[216:219], v[28:31]
	v_mfma_f32_16x16x32_bf16 v[32:35], v[168:171], v[216:219], v[32:35]
	v_mfma_f32_16x16x32_bf16 v[80:83], v[172:175], v[188:191], v[80:83]
	v_mfma_f32_16x16x32_bf16 v[72:75], v[176:179], v[188:191], v[72:75]
	v_mfma_f32_16x16x32_bf16 v[64:67], v[172:175], v[192:195], v[64:67]
	v_mfma_f32_16x16x32_bf16 v[56:59], v[176:179], v[192:195], v[56:59]
	v_mfma_f32_16x16x32_bf16 v[48:51], v[172:175], v[220:223], v[48:51]
	v_mfma_f32_16x16x32_bf16 v[40:43], v[176:179], v[220:223], v[40:43]
	v_mfma_f32_16x16x32_bf16 v[28:31], v[172:175], v[224:227], v[28:31]
	v_mfma_f32_16x16x32_bf16 v[32:35], v[176:179], v[224:227], v[32:35]
	s_setprio 0
	s_barrier
	s_add_i32 s85, 0, 0x18000
	v_add_u32_e32 v3, s85, v208
	v_add_u32_e32 v144, s85, v209
	s_add_i32 s85, 0, 0x1c000
	ds_read_b128 v[116:119], v3
	ds_read_b128 v[120:123], v3 offset:2048
	ds_read_b128 v[140:143], v144
	ds_read_b128 v[144:147], v144 offset:2048
	v_add_u32_e32 v3, s85, v208
	v_add_u32_e32 v176, s85, v209
	ds_read_b128 v[164:167], v3
	ds_read_b128 v[168:171], v3 offset:2048
	ds_read_b128 v[172:175], v176
	ds_read_b128 v[176:179], v176 offset:2048
	s_add_i32 s84, s84, s29
	s_mov_b32 m0, s39
	ds_read_b128 v[180:183], v214 offset:32768
	ds_read_b128 v[184:187], v214 offset:34816
	ds_read_b128 v[188:191], v215 offset:32768
	ds_read_b128 v[192:195], v215 offset:34816
	ds_read_b128 v[196:199], v214 offset:36864
	ds_read_b128 v[216:219], v214 offset:38912
	ds_read_b128 v[220:223], v215 offset:36864
	ds_read_b128 v[224:227], v215 offset:38912
	buffer_load_dwordx4 v204, s[48:51], s84 offen lds
	s_mov_b32 m0, s40
	s_nop 0
	buffer_load_dwordx4 v206, s[48:51], s84 offen lds
	s_waitcnt vmcnt(8)
	s_waitcnt lgkmcnt(0)
	s_barrier
	s_setprio 1
	s_waitcnt lgkmcnt(0)
	v_mfma_f32_16x16x32_bf16 v[160:163], v[116:119], v[180:183], v[160:163]
	v_mfma_f32_16x16x32_bf16 v[152:155], v[120:123], v[180:183], v[152:155]
	v_mfma_f32_16x16x32_bf16 v[132:135], v[116:119], v[184:187], v[132:135]
	v_mfma_f32_16x16x32_bf16 v[124:127], v[120:123], v[184:187], v[124:127]
	v_mfma_f32_16x16x32_bf16 v[108:111], v[116:119], v[196:199], v[108:111]
	v_mfma_f32_16x16x32_bf16 v[100:103], v[120:123], v[196:199], v[100:103]
	v_mfma_f32_16x16x32_bf16 v[92:95], v[116:119], v[216:219], v[92:95]
	v_mfma_f32_16x16x32_bf16 v[84:87], v[120:123], v[216:219], v[84:87]
	v_mfma_f32_16x16x32_bf16 v[160:163], v[140:143], v[188:191], v[160:163]
	v_mfma_f32_16x16x32_bf16 v[152:155], v[144:147], v[188:191], v[152:155]
	v_mfma_f32_16x16x32_bf16 v[132:135], v[140:143], v[192:195], v[132:135]
	v_mfma_f32_16x16x32_bf16 v[124:127], v[144:147], v[192:195], v[124:127]
	v_mfma_f32_16x16x32_bf16 v[108:111], v[140:143], v[220:223], v[108:111]
	v_mfma_f32_16x16x32_bf16 v[100:103], v[144:147], v[220:223], v[100:103]
	v_mfma_f32_16x16x32_bf16 v[92:95], v[140:143], v[224:227], v[92:95]
	v_mfma_f32_16x16x32_bf16 v[84:87], v[144:147], v[224:227], v[84:87]
	s_setprio 0
	s_setprio 1
	v_mfma_f32_16x16x32_bf16 v[156:159], v[164:167], v[180:183], v[156:159]
	v_mfma_f32_16x16x32_bf16 v[148:151], v[168:171], v[180:183], v[148:151]
	v_mfma_f32_16x16x32_bf16 v[136:139], v[164:167], v[184:187], v[136:139]
	v_mfma_f32_16x16x32_bf16 v[128:131], v[168:171], v[184:187], v[128:131]
	v_mfma_f32_16x16x32_bf16 v[112:115], v[164:167], v[196:199], v[112:115]
	v_mfma_f32_16x16x32_bf16 v[104:107], v[168:171], v[196:199], v[104:107]
	v_mfma_f32_16x16x32_bf16 v[96:99], v[164:167], v[216:219], v[96:99]
	v_mfma_f32_16x16x32_bf16 v[88:91], v[168:171], v[216:219], v[88:91]
	v_mfma_f32_16x16x32_bf16 v[156:159], v[172:175], v[188:191], v[156:159]
	v_mfma_f32_16x16x32_bf16 v[148:151], v[176:179], v[188:191], v[148:151]
	v_mfma_f32_16x16x32_bf16 v[136:139], v[172:175], v[192:195], v[136:139]
	v_mfma_f32_16x16x32_bf16 v[128:131], v[176:179], v[192:195], v[128:131]
	v_mfma_f32_16x16x32_bf16 v[112:115], v[172:175], v[220:223], v[112:115]
	v_mfma_f32_16x16x32_bf16 v[104:107], v[176:179], v[220:223], v[104:107]
	v_mfma_f32_16x16x32_bf16 v[96:99], v[172:175], v[224:227], v[96:99]
	v_mfma_f32_16x16x32_bf16 v[88:91], v[176:179], v[224:227], v[88:91]
	s_setprio 0
	s_barrier
	s_mov_b32 m0, s41
	ds_read_b128 v[180:183], v214 offset:49152
	ds_read_b128 v[184:187], v214 offset:51200
	ds_read_b128 v[188:191], v215 offset:49152
	ds_read_b128 v[192:195], v215 offset:51200
	ds_read_b128 v[196:199], v214 offset:53248
	ds_read_b128 v[216:219], v214 offset:55296
	ds_read_b128 v[220:223], v215 offset:53248
	ds_read_b128 v[224:227], v215 offset:55296
	buffer_load_dwordx4 v205, s[8:11], s82 offen lds
	s_mov_b32 m0, s42
	s_nop 0
	buffer_load_dwordx4 v207, s[8:11], s82 offen lds
	s_add_i32 s82, s82, s29
	s_mov_b32 m0, s45
	s_nop 0
	buffer_load_dwordx4 v205, s[8:11], s82 offen lds
	s_mov_b32 m0, s46
	s_nop 0
	buffer_load_dwordx4 v207, s[8:11], s82 offen lds
	s_mov_b32 m0, s43
	s_nop 0
	buffer_load_dwordx4 v204, s[48:51], s81 offen lds
	s_mov_b32 m0, s44
	s_nop 0
	buffer_load_dwordx4 v206, s[48:51], s81 offen lds
	s_waitcnt vmcnt(8)
	s_waitcnt lgkmcnt(0)
	s_barrier
	s_setprio 1
	s_waitcnt lgkmcnt(0)
	v_mfma_f32_16x16x32_bf16 v[76:79], v[116:119], v[180:183], v[76:79]
	v_mfma_f32_16x16x32_bf16 v[68:71], v[120:123], v[180:183], v[68:71]
	v_mfma_f32_16x16x32_bf16 v[60:63], v[116:119], v[184:187], v[60:63]
	v_mfma_f32_16x16x32_bf16 v[52:55], v[120:123], v[184:187], v[52:55]
	v_mfma_f32_16x16x32_bf16 v[44:47], v[116:119], v[196:199], v[44:47]
	v_mfma_f32_16x16x32_bf16 v[36:39], v[120:123], v[196:199], v[36:39]
	v_mfma_f32_16x16x32_bf16 v[24:27], v[116:119], v[216:219], v[24:27]
	v_mfma_f32_16x16x32_bf16 v[20:23], v[120:123], v[216:219], v[20:23]
	v_mfma_f32_16x16x32_bf16 v[76:79], v[140:143], v[188:191], v[76:79]
	v_mfma_f32_16x16x32_bf16 v[68:71], v[144:147], v[188:191], v[68:71]
	v_mfma_f32_16x16x32_bf16 v[60:63], v[140:143], v[192:195], v[60:63]
	v_mfma_f32_16x16x32_bf16 v[52:55], v[144:147], v[192:195], v[52:55]
	v_mfma_f32_16x16x32_bf16 v[44:47], v[140:143], v[220:223], v[44:47]
	v_mfma_f32_16x16x32_bf16 v[36:39], v[144:147], v[220:223], v[36:39]
	v_mfma_f32_16x16x32_bf16 v[24:27], v[140:143], v[224:227], v[24:27]
	v_mfma_f32_16x16x32_bf16 v[20:23], v[144:147], v[224:227], v[20:23]
	s_setprio 0
	s_setprio 1
	v_mfma_f32_16x16x32_bf16 v[80:83], v[164:167], v[180:183], v[80:83]
	v_mfma_f32_16x16x32_bf16 v[72:75], v[168:171], v[180:183], v[72:75]
	v_mfma_f32_16x16x32_bf16 v[64:67], v[164:167], v[184:187], v[64:67]
	v_mfma_f32_16x16x32_bf16 v[56:59], v[168:171], v[184:187], v[56:59]
	v_mfma_f32_16x16x32_bf16 v[48:51], v[164:167], v[196:199], v[48:51]
	v_mfma_f32_16x16x32_bf16 v[40:43], v[168:171], v[196:199], v[40:43]
	v_mfma_f32_16x16x32_bf16 v[28:31], v[164:167], v[216:219], v[28:31]
	v_mfma_f32_16x16x32_bf16 v[32:35], v[168:171], v[216:219], v[32:35]
	v_mfma_f32_16x16x32_bf16 v[80:83], v[172:175], v[188:191], v[80:83]
	v_mfma_f32_16x16x32_bf16 v[72:75], v[176:179], v[188:191], v[72:75]
	v_mfma_f32_16x16x32_bf16 v[64:67], v[172:175], v[192:195], v[64:67]
	v_mfma_f32_16x16x32_bf16 v[56:59], v[176:179], v[192:195], v[56:59]
	v_mfma_f32_16x16x32_bf16 v[48:51], v[172:175], v[220:223], v[48:51]
	v_mfma_f32_16x16x32_bf16 v[40:43], v[176:179], v[220:223], v[40:43]
	v_mfma_f32_16x16x32_bf16 v[28:31], v[172:175], v[224:227], v[28:31]
	v_mfma_f32_16x16x32_bf16 v[32:35], v[176:179], v[224:227], v[32:35]
	s_setprio 0
	s_barrier
.Lc0r_tail:
	s_add_i32 s78, s78, 2
	s_addk_i32 s64, 0x100
	s_addk_i32 s65, 0x100
	s_cmp_ge_u32 s78, s47
	s_cbranch_scc1 .LBB0_385

.LBB0_403:
	s_or_b64 exec, exec, s[10:11]
	s_andn2_b64 vcc, exec, s[4:5]
	s_mov_b64 s[4:5], -1
	s_waitcnt vmcnt(0)
	s_cbranch_vccnz .LBB0_374
	s_waitcnt lgkmcnt(0)
	v_mov_b32_e32 v2, v1
	v_mov_b32_e32 v3, v1
	v_mov_b32_e32 v0, v1
	v_mov_b64_e32 v[34:35], v[2:3]
	v_mov_b64_e32 v[32:33], v[0:1]
	s_andn2_b64 vcc, exec, s[14:15]
	s_cbranch_vccnz .LBB0_373
	s_barrier
	s_branch .LBB0_373
